# attention: V rows staged unpermuted so P needs no cross-half permlane swaps; cross-half row-max combine only on the rare rescale path
# baseline (speedup 1.0000x reference)
; __device__ __forceinline__ unsigned f2bf(float f) { unsigned u = __builtin_bit_cast(unsigned, f); return (u + 0x7fffu + ((u >> 16) & 1u)) >> 16; }
; __device__ __forceinline__ int v_rd_base(int lane) { return ((lane & 3) << 3) | (((lane >> 2) & 3) << 6) | (((lane >> 4) & 1) << 5) | (((lane >> 5) & 1) << 8); }
; #define SWAIT() asm volatile("s_waitcnt vmcnt(0)" ::: "memory")
; __device__ __forceinline__ int v_st(int k, int c) { const int kk = (k & ~0xC) | ((k & 4) << 1) | ((k & 8) >> 1); return ((kk >> 3) * 4 + (c >> 5)) * 512 + ((kk & 7) * 32 + (c & 31)) * 2; }
; __device__ __forceinline__ void attn_item(const bf16_t* __restrict__ Qb, const bf16_t* __restrict__ Kn, const bf16_t* __restrict__ Kr, const bf16_t* __restrict__ Vh,
;                                           const float* __restrict__ csq, bf16_t* __restrict__ Ob, int seq, char* lds) {
;     ...
;   const bf16_t* Qw = Qb + (long)(wid * QBLK + r32) * 1792 + hi * 8;
; #pragma unroll
;   for (int d0 = 0; d0 < 6; ++d0) qr[d0] = *reinterpret_cast<const bf16x8*>(Qw + d0 * 16);
;   { const float* cp = csq + (long)(wid * QBLK + r32) * 32 + hi * 8;
;     const f32x4 c0 = *(const f32x4*)cp, c1 = *(const f32x4*)(cp + 4), s0 = *(const f32x4*)(cp + 16), s1 = *(const f32x4*)(cp + 20);
;     float cc[8] = {c0[0], c0[1], c0[2], c0[3], c1[0], c1[1], c1[2], c1[3]}, ss[8] = {s0[0], s0[1], s0[2], s0[3], s1[0], s1[1], s1[2], s1[3]};
;     bf16x8 n4, n5;
; #pragma unroll
;     for (int e = 0; e < 8; ++e) { const float x1 = bf2f((unsigned short)qr[4][e]), x2 = bf2f((unsigned short)qr[5][e]);
;       n4[e] = (short)f2bf(x1 * cc[e] - x2 * ss[e]); n5[e] = (short)f2bf(x1 * ss[e] + x2 * cc[e]); }
;     qr[4] = n4; qr[5] = n5; }
;   const int sr = tid >> 3, sc = (tid & 7) * 8, vst0 = v_st(sr, sc);
;   const int rr_ = (tid & 255) >> 2, rc_ = (tid & 3) * 8;
;   const int vb0 = (int)(uintptr_t)V_lds + v_rd_base(lane);
;   struct { bf16x8 vs, kn, kr; } sr_[1];
;     ...
;   f32x16 pA0, pA1, pB0, pB1; float alA, alB; bf16x8 pa0, pa1, pa2, pa3; const int NT = seq / KVBLK;
;   int sp = 0, scu = 0, sn = SLOT;
;     ...
;   if (__builtin_amdgcn_readfirstlane(wid) >= 4) __builtin_amdgcn_s_setprio(1);
;   __syncthreads();
;   SLOAD(0, 0); SWAIT(); SWRITE(0, 0); __syncthreads();
;   qkt(pA0, pA1, K_lds, qr, negm, r32, hi); partialSM<true>(pA0, pA1, mhat, negm, alA);
;   SLOAD(0, KVBLK); SWAIT(); SWRITE(SLOT, 0); __syncthreads();
.Lat_item:
	s_lshr_b32 s0, s28, 5
	s_and_b32 s1, s28, 31
	s_lshr_b32 s2, s0, 3
	s_and_b32 s0, s0, 7
	s_mul_i32 s10, s2, 0x1c00000
	s_add_u32 s16, s14, 0xd600000
	s_addc_u32 s17, s15, 0
	s_add_u32 s16, s16, s10
	s_addc_u32 s17, s17, 0
	s_mul_i32 s11, s1, 0xe0000
	s_mul_i32 s30, s0, 192
	s_add_i32 s11, s11, s30
	s_add_u32 s16, s16, s11
	s_addc_u32 s17, s17, 0
	s_lshl_b32 s30, s2, 13
	s_lshl_b32 s31, s1, 8
	s_add_i32 s30, s30, s31
	s_lshl_b32 s31, s30, 7
	s_add_u32 s18, s14, 0x5100000
	s_addc_u32 s19, s15, 0
	s_add_u32 s18, s18, s31
	s_addc_u32 s19, s19, 0
	s_lshl_b32 s31, s30, 11
	s_lshl_b32 s11, s0, 7
	s_add_i32 s31, s31, s11
	s_add_u32 s26, s12, s31
	s_addc_u32 s27, s13, 0
	s_lshl_b32 s11, s0, 8
	s_add_i32 s10, s10, s11
	s_add_i32 s10, s10, 0xd600600
	s_lshl_b32 s11, s2, 19
	s_add_i32 s11, s11, 0x1de00000
	v_and_b32_e32 v1, 63, v180
	v_and_b32_e32 v178, 31, v1
	v_lshrrev_b32_e32 v179, 5, v1
	s_lshl_b32 s30, s29, 5
	v_add_u32_e32 v213, s30, v178
	s_movk_i32 s31, 0xe00
	v_mul_lo_u32 v214, v213, s31
	v_lshl_add_u32 v214, v179, 4, v214
	v_lshlrev_b32_e32 v215, 7, v213
	v_lshl_add_u32 v215, v179, 5, v215
	s_barrier
	global_load_dwordx4 v[114:117], v214, s[16:17] offset:0
	global_load_dwordx4 v[118:121], v214, s[16:17] offset:32
	global_load_dwordx4 v[122:125], v214, s[16:17] offset:64
	global_load_dwordx4 v[126:129], v214, s[16:17] offset:96
	global_load_dwordx4 v[130:133], v214, s[16:17] offset:128
	global_load_dwordx4 v[134:137], v214, s[16:17] offset:160
	global_load_dwordx4 v[34:37], v215, s[18:19]
	global_load_dwordx4 v[38:41], v215, s[18:19] offset:16
	global_load_dwordx4 v[42:45], v215, s[18:19] offset:64
	global_load_dwordx4 v[46:49], v215, s[18:19] offset:80
	v_and_b32_e32 v213, 15, v1
	v_lshrrev_b32_e32 v214, 4, v1
	s_lshl_b32 s30, s29, 3
	v_add_u32_e32 v214, s30, v214
	v_add_u32_e32 v215, 0, v214
	v_and_b32_e32 v216, 15, v215
	v_xor_b32_e32 v216, v213, v216
	v_cmp_gt_u32_e32 vcc, 8, v216
	v_and_b32_e32 v217, 7, v216
	v_mov_b32_e32 v177, 64
	v_mov_b32_e32 v1, 0xe00
	v_cndmask_b32_e32 v177, v177, v1, vcc
	v_mul_lo_u32 v177, v215, v177
	v_lshl_add_u32 v177, v217, 4, v177
	v_mov_b32_e32 v1, s11
	v_mov_b32_e32 v217, s10
	v_cndmask_b32_e32 v1, v1, v217, vcc
	v_add_u32_e32 v146, v177, v1
	v_mov_b32_e32 v1, 0x1000
	v_mov_b32_e32 v217, 0x38000
	v_cndmask_b32_e32 v148, v1, v217, vcc
	v_add_u32_e32 v215, 4, v214
	v_and_b32_e32 v216, 15, v215
	v_xor_b32_e32 v216, v213, v216
	v_cmp_gt_u32_e32 vcc, 8, v216
	v_and_b32_e32 v217, 7, v216
	v_mov_b32_e32 v177, 64
	v_mov_b32_e32 v1, 0xe00
	v_cndmask_b32_e32 v177, v177, v1, vcc
	v_mul_lo_u32 v177, v215, v177
	v_lshl_add_u32 v177, v217, 4, v177
	v_mov_b32_e32 v1, s11
	v_mov_b32_e32 v217, s10
	v_cndmask_b32_e32 v1, v1, v217, vcc
	v_add_u32_e32 v147, v177, v1
	v_mov_b32_e32 v1, 0x1000
	v_mov_b32_e32 v217, 0x38000
	v_cndmask_b32_e32 v217, v1, v217, vcc
	v_and_b32_e32 v1, 63, v180
	v_bfe_u32 v213, v1, 2, 3
	v_add_u32_e32 v213, s30, v213
	s_movk_i32 s31, 0xe00
	v_mul_lo_u32 v213, v213, s31
	v_and_b32_e32 v214, 3, v1
	v_lshl_add_u32 v213, v214, 4, v213
	v_lshrrev_b32_e32 v214, 5, v1
	v_lshl_add_u32 v213, v214, 6, v213
	s_add_i32 s31, s10, 128
	v_add_u32_e32 v149, s31, v213
	s_add_i32 m0, s6, 0
	s_mov_b64 exec, s[20:21]
	global_load_lds_dwordx4 v146, s[14:15]
	s_add_i32 m0, s6, 1024
	s_mov_b64 exec, s[22:23]
	global_load_lds_dwordx4 v147, s[14:15]
	s_mov_b64 exec, -1
	v_add_u32_e32 v146, v146, v148
	v_add_u32_e32 v147, v147, v217
	s_add_i32 m0, s6, 16384
	s_mov_b64 exec, s[20:21]
	global_load_lds_dwordx4 v146, s[14:15]
	s_add_i32 m0, s6, 17408
	s_mov_b64 exec, s[22:23]
	global_load_lds_dwordx4 v147, s[14:15]
	s_mov_b64 exec, -1
	v_add_u32_e32 v146, v146, v148
	v_add_u32_e32 v147, v147, v217
	s_add_i32 m0, s6, 32768
	s_mov_b64 exec, s[20:21]
	global_load_lds_dwordx4 v146, s[14:15]
	s_add_i32 m0, s6, 33792
	s_mov_b64 exec, s[22:23]
	global_load_lds_dwordx4 v147, s[14:15]
	s_mov_b64 exec, -1
	v_add_u32_e32 v146, v146, v148
	v_add_u32_e32 v147, v147, v217
	s_add_i32 m0, s7, 0
	s_nop 0
	global_load_lds_dwordx4 v149, s[14:15]
	v_add_u32_e32 v149, 0x38000, v149
	s_add_i32 m0, s6, 49152
	s_mov_b64 exec, s[20:21]
	global_load_lds_dwordx4 v146, s[14:15]
	s_add_i32 m0, s6, 50176
	s_mov_b64 exec, s[22:23]
	global_load_lds_dwordx4 v147, s[14:15]
	s_mov_b64 exec, -1
	v_add_u32_e32 v146, v146, v148
	v_add_u32_e32 v147, v147, v217
	s_add_i32 m0, s7, 16384
	s_nop 0
	global_load_lds_dwordx4 v149, s[14:15]
	v_add_u32_e32 v149, 0x38000, v149
	v_mov_b64_e32 v[2:3], 0
	v_mov_b64_e32 v[4:5], 0
	v_mov_b64_e32 v[6:7], 0
	v_mov_b64_e32 v[8:9], 0
	v_mov_b64_e32 v[10:11], 0
	v_mov_b64_e32 v[12:13], 0
	v_mov_b64_e32 v[14:15], 0
	v_mov_b64_e32 v[16:17], 0
	v_mov_b64_e32 v[18:19], 0
	v_mov_b64_e32 v[20:21], 0
	v_mov_b64_e32 v[22:23], 0
	v_mov_b64_e32 v[24:25], 0
	v_mov_b64_e32 v[26:27], 0
	v_mov_b64_e32 v[28:29], 0
	v_mov_b64_e32 v[30:31], 0
	v_mov_b64_e32 v[32:33], 0
	v_mov_b32_e32 v174, 0
	s_waitcnt vmcnt(10)
	v_lshlrev_b32_e32 v66, 16, v130
	v_and_b32_e32 v67, 0xffff0000, v130
	v_lshlrev_b32_e32 v68, 16, v131
	v_and_b32_e32 v69, 0xffff0000, v131
	v_lshlrev_b32_e32 v70, 16, v132
	v_and_b32_e32 v71, 0xffff0000, v132
	v_lshlrev_b32_e32 v72, 16, v133
	v_and_b32_e32 v73, 0xffff0000, v133
	v_lshlrev_b32_e32 v74, 16, v134
	v_and_b32_e32 v75, 0xffff0000, v134
	v_lshlrev_b32_e32 v76, 16, v135
	v_and_b32_e32 v77, 0xffff0000, v135
	v_lshlrev_b32_e32 v78, 16, v136
	v_and_b32_e32 v79, 0xffff0000, v136
	v_lshlrev_b32_e32 v80, 16, v137
	v_and_b32_e32 v81, 0xffff0000, v137
	v_mul_f32_e32 v82, v74, v42
	v_mul_f32_e32 v90, v66, v42
	v_mul_f32_e32 v83, v75, v43
	v_mul_f32_e32 v91, v67, v43
	v_mul_f32_e32 v84, v76, v44
	v_mul_f32_e32 v92, v68, v44
	v_mul_f32_e32 v85, v77, v45
	v_mul_f32_e32 v93, v69, v45
	v_mul_f32_e32 v86, v78, v46
	v_mul_f32_e32 v94, v70, v46
	v_mul_f32_e32 v87, v79, v47
	v_mul_f32_e32 v95, v71, v47
	v_mul_f32_e32 v88, v80, v48
	v_mul_f32_e32 v96, v72, v48
	v_mul_f32_e32 v89, v81, v49
	v_mul_f32_e32 v97, v73, v49
	v_fma_f32 v82, v66, v34, -v82
	v_fma_f32 v90, v74, v34, v90
	v_fma_f32 v83, v67, v35, -v83
	v_fma_f32 v91, v75, v35, v91
	v_fma_f32 v84, v68, v36, -v84
	v_fma_f32 v92, v76, v36, v92
	v_fma_f32 v85, v69, v37, -v85
	v_fma_f32 v93, v77, v37, v93
	v_fma_f32 v86, v70, v38, -v86
	v_fma_f32 v94, v78, v38, v94
	v_fma_f32 v87, v71, v39, -v87
	v_fma_f32 v95, v79, v39, v95
	v_fma_f32 v88, v72, v40, -v88
	v_fma_f32 v96, v80, v40, v96
	v_fma_f32 v89, v73, v41, -v89
	v_fma_f32 v97, v81, v41, v97
	v_cvt_pk_bf16_f32 v130, v82, v83
	v_cvt_pk_bf16_f32 v134, v90, v91
	v_cvt_pk_bf16_f32 v131, v84, v85
	v_cvt_pk_bf16_f32 v135, v92, v93
	v_cvt_pk_bf16_f32 v132, v86, v87
	v_cvt_pk_bf16_f32 v136, v94, v95
	v_cvt_pk_bf16_f32 v133, v88, v89
	v_cvt_pk_bf16_f32 v137, v96, v97
	s_waitcnt vmcnt(8)
	s_barrier
; template <bool FIRST> __device__ __forceinline__ void partialSM(f32x16& p0, f32x16& p1, float& mhat, f32x16& negm, float& alpha) {
;   float pa = fmaxf(fmaxf(p0[0], p0[1]), p1[0]), pb = fmaxf(fmaxf(p0[2], p0[3]), p1[1]); pa = fmaxf(fmaxf(pa, p1[2]), p1[3]);
; #pragma unroll
;   for (int r = 4; r < 16; r += 4) { pa = fmaxf(fmaxf(pa, p0[r]), p0[r + 1]); pb = fmaxf(fmaxf(pb, p0[r + 2]), p0[r + 3]); pa = fmaxf(fmaxf(pa, p1[r]), p1[r + 1]); pb = fmaxf(fmaxf(pb, p1[r + 2]), p1[r + 3]); }
;   float pmax = fmaxf(pa, pb);
;   { auto rr = __builtin_amdgcn_permlane32_swap(__float_as_uint(pmax), __float_as_uint(pmax), false, false);
;     pmax = fmaxf(__uint_as_float(rr[0]), __uint_as_float(rr[1])); }
;   if (!FIRST && __builtin_expect(__all(pmax <= THRL), 1)) { alpha = 1.f; }
;   else { const float d = FIRST ? pmax : fmaxf(pmax, 0.f); mhat += d; alpha = FIRST ? 1.f : __builtin_amdgcn_exp2f(-d);
; #pragma unroll
;     for (int r = 0; r < 16; ++r) { p0[r] -= d; p1[r] -= d; }
; #pragma unroll
;     for (int r = 0; r < 16; ++r) negm[r] = -mhat; }
; #pragma unroll
;   for (int r = 0; r < 16; ++r) p0[r] = __builtin_amdgcn_exp2f(p0[r]);
; }
; __device__ __forceinline__ void finishSM(f32x16& p0, f32x16& p1, float alpha, float& l_reg, bf16x8& pa0, bf16x8& pa1, bf16x8& pa2, bf16x8& pa3) {
; #pragma unroll
;   for (int r = 0; r < 16; ++r) p1[r] = __builtin_amdgcn_exp2f(p1[r]);
;   float ps = 0;
; #pragma unroll
;   for (int r = 0; r < 16; ++r) ps += p0[r];
; #pragma unroll
;   for (int r = 0; r < 16; ++r) ps += p1[r];
;   { auto rr = __builtin_amdgcn_permlane32_swap(__float_as_uint(ps), __float_as_uint(ps), false, false);
;     ps = __uint_as_float(rr[0]) + __uint_as_float(rr[1]); }
;   l_reg = l_reg * alpha + ps;
;     ...
;   PK4(p0, 0, pa0); PK4(p0, 8, pa1); PK4(p1, 0, pa2); PK4(p1, 8, pa3);
;     ...
; }
; __device__ __forceinline__ void qkt(f32x16& p0, f32x16& p1, const bf16_t* Ks, const bf16x8* qr, const f32x16& negm, int r32, int hi) {
;   p0 = negm; p1 = negm;
; #pragma unroll
;   for (int d0 = 0; d0 < 6; ++d0) { int cb = (d0 * 16 + hi * 8) * 2;
;     bf16x8 b0 = *reinterpret_cast<const bf16x8*>((const char*)Ks + KSWZ(r32, cb));
;     bf16x8 b1 = *reinterpret_cast<const bf16x8*>((const char*)Ks + KSWZ(32 + r32, cb));
;     p0 = __builtin_amdgcn_mfma_f32_32x32x16_bf16(b0, qr[d0], p0, 0, 0, 0);
;     p1 = __builtin_amdgcn_mfma_f32_32x32x16_bf16(b1, qr[d0], p1, 0, 0, 0); }
; }
	ds_read_b128 v[184:187], v140 offset:0
	ds_read_b128 v[188:191], v140 offset:8192
	ds_read_b128 v[192:195], v141 offset:0
	ds_read_b128 v[196:199], v141 offset:8192
	ds_read_b128 v[200:203], v142 offset:0
	ds_read_b128 v[204:207], v142 offset:8192
	ds_read_b128 v[208:211], v143 offset:0
	ds_read_b128 v[212:215], v143 offset:8192
	s_waitcnt lgkmcnt(7)
	v_mfma_f32_32x32x16_bf16 v[34:49], v[184:187], v[114:117], 0
	ds_read_b128 v[184:187], v144 offset:0
	s_waitcnt lgkmcnt(7)
	v_mfma_f32_32x32x16_bf16 v[50:65], v[188:191], v[114:117], 0
	ds_read_b128 v[188:191], v144 offset:8192
	s_waitcnt lgkmcnt(7)
	v_mfma_f32_32x32x16_bf16 v[34:49], v[192:195], v[118:121], v[34:49]
	ds_read_b128 v[192:195], v145 offset:0
	s_waitcnt lgkmcnt(7)
	v_mfma_f32_32x32x16_bf16 v[50:65], v[196:199], v[118:121], v[50:65]
	ds_read_b128 v[196:199], v145 offset:8192
	s_waitcnt lgkmcnt(7)
	v_mfma_f32_32x32x16_bf16 v[34:49], v[200:203], v[122:125], v[34:49]
	s_waitcnt lgkmcnt(6)
	v_mfma_f32_32x32x16_bf16 v[50:65], v[204:207], v[122:125], v[50:65]
	s_waitcnt lgkmcnt(5)
	v_mfma_f32_32x32x16_bf16 v[34:49], v[208:211], v[126:129], v[34:49]
	s_waitcnt lgkmcnt(4)
	v_mfma_f32_32x32x16_bf16 v[50:65], v[212:215], v[126:129], v[50:65]
	s_waitcnt lgkmcnt(3)
	v_mfma_f32_32x32x16_bf16 v[34:49], v[184:187], v[130:133], v[34:49]
	s_waitcnt lgkmcnt(2)
	v_mfma_f32_32x32x16_bf16 v[50:65], v[188:191], v[130:133], v[50:65]
	s_waitcnt lgkmcnt(1)
	v_mfma_f32_32x32x16_bf16 v[34:49], v[192:195], v[134:137], v[34:49]
	s_waitcnt lgkmcnt(0)
	v_mfma_f32_32x32x16_bf16 v[50:65], v[196:199], v[134:137], v[50:65]
	s_nop 9
	v_max3_f32 v177, v34, v35, v36
	v_max3_f32 v178, v37, v38, v39
	v_max3_f32 v177, v177, v40, v41
	v_max3_f32 v178, v178, v42, v43
	v_max3_f32 v177, v177, v44, v45
	v_max3_f32 v178, v178, v46, v47
	v_max3_f32 v177, v177, v48, v49
	v_max3_f32 v178, v178, v50, v51
	v_max3_f32 v177, v177, v52, v53
	v_max3_f32 v178, v178, v54, v55
	v_max3_f32 v177, v177, v56, v57
	v_max3_f32 v178, v178, v58, v59
	v_max3_f32 v177, v177, v60, v61
	v_max3_f32 v178, v178, v62, v63
	v_max3_f32 v177, v177, v64, v65
	v_max_f32_e32 v177, v177, v178
	v_mov_b32_e32 v178, v177
	s_nop 1
	v_permlane32_swap_b32_e32 v177, v178
	v_max_f32_e32 v177, v177, v178
	v_mov_b32_e32 v151, v177
	v_sub_f32_e32 v34, v34, v177
	v_sub_f32_e32 v35, v35, v177
	v_sub_f32_e32 v36, v36, v177
	v_sub_f32_e32 v37, v37, v177
	v_sub_f32_e32 v38, v38, v177
	v_sub_f32_e32 v39, v39, v177
	v_sub_f32_e32 v40, v40, v177
	v_sub_f32_e32 v41, v41, v177
	v_sub_f32_e32 v42, v42, v177
	v_sub_f32_e32 v43, v43, v177
	v_sub_f32_e32 v44, v44, v177
	v_sub_f32_e32 v45, v45, v177
	v_sub_f32_e32 v46, v46, v177
	v_sub_f32_e32 v47, v47, v177
	v_sub_f32_e32 v48, v48, v177
	v_sub_f32_e32 v49, v49, v177
	v_sub_f32_e32 v50, v50, v177
	v_sub_f32_e32 v51, v51, v177
	v_sub_f32_e32 v52, v52, v177
	v_sub_f32_e32 v53, v53, v177
	v_sub_f32_e32 v54, v54, v177
	v_sub_f32_e32 v55, v55, v177
	v_sub_f32_e32 v56, v56, v177
	v_sub_f32_e32 v57, v57, v177
	v_sub_f32_e32 v58, v58, v177
	v_sub_f32_e32 v59, v59, v177
	v_sub_f32_e32 v60, v60, v177
	v_sub_f32_e32 v61, v61, v177
	v_sub_f32_e32 v62, v62, v177
	v_sub_f32_e32 v63, v63, v177
	v_sub_f32_e32 v64, v64, v177
	v_sub_f32_e32 v65, v65, v177
	v_xor_b32_e32 v98, 0x80000000, v151
	v_mov_b32_e32 v99, v98
	v_mov_b32_e32 v100, v98
	v_mov_b32_e32 v101, v98
	v_mov_b32_e32 v102, v98
	v_mov_b32_e32 v103, v98
	v_mov_b32_e32 v104, v98
	v_mov_b32_e32 v105, v98
	v_mov_b32_e32 v106, v98
	v_mov_b32_e32 v107, v98
	v_mov_b32_e32 v108, v98
	v_mov_b32_e32 v109, v98
	v_mov_b32_e32 v110, v98
	v_mov_b32_e32 v111, v98
	v_mov_b32_e32 v112, v98
	v_mov_b32_e32 v113, v98
	v_exp_f32_e32 v34, v34
	v_exp_f32_e32 v35, v35
	v_exp_f32_e32 v36, v36
	v_exp_f32_e32 v37, v37
	v_exp_f32_e32 v38, v38
	v_exp_f32_e32 v39, v39
	v_exp_f32_e32 v40, v40
	v_exp_f32_e32 v41, v41
	v_exp_f32_e32 v42, v42
	v_exp_f32_e32 v43, v43
	v_exp_f32_e32 v44, v44
	v_exp_f32_e32 v45, v45
	v_exp_f32_e32 v46, v46
	v_exp_f32_e32 v47, v47
	v_exp_f32_e32 v48, v48
	v_exp_f32_e32 v49, v49
	v_add_f32_e32 v181, v34, v38
	v_add_f32_e32 v182, v35, v39
	v_add_f32_e32 v183, v36, v40
	v_add_f32_e32 v216, v37, v41
	v_add_f32_e32 v181, v181, v42
	v_add_f32_e32 v182, v182, v43
	v_add_f32_e32 v183, v183, v44
	v_add_f32_e32 v216, v216, v45
	v_add_f32_e32 v181, v181, v46
	v_add_f32_e32 v182, v182, v47
	v_add_f32_e32 v183, v183, v48
	v_add_f32_e32 v216, v216, v49
	s_waitcnt vmcnt(3)
	s_barrier
	ds_read_b128 v[184:187], v140 offset:16384
	ds_read_b128 v[188:191], v140 offset:24576
	ds_read_b128 v[192:195], v141 offset:16384
	ds_read_b128 v[196:199], v141 offset:24576
	s_mov_b32 s8, 0
; template <bool FIRST> __device__ __forceinline__ void partialSM(f32x16& p0, f32x16& p1, float& mhat, f32x16& negm, float& alpha) {
;   float pa = fmaxf(fmaxf(p0[0], p0[1]), p1[0]), pb = fmaxf(fmaxf(p0[2], p0[3]), p1[1]); pa = fmaxf(fmaxf(pa, p1[2]), p1[3]);
; #pragma unroll
;   for (int r = 4; r < 16; r += 4) { pa = fmaxf(fmaxf(pa, p0[r]), p0[r + 1]); pb = fmaxf(fmaxf(pb, p0[r + 2]), p0[r + 3]); pa = fmaxf(fmaxf(pa, p1[r]), p1[r + 1]); pb = fmaxf(fmaxf(pb, p1[r + 2]), p1[r + 3]); }
;   float pmax = fmaxf(pa, pb);
;   { auto rr = __builtin_amdgcn_permlane32_swap(__float_as_uint(pmax), __float_as_uint(pmax), false, false);
;     pmax = fmaxf(__uint_as_float(rr[0]), __uint_as_float(rr[1])); }
;   if (!FIRST && __builtin_expect(__all(pmax <= THRL), 1)) { alpha = 1.f; }
;   else { const float d = FIRST ? pmax : fmaxf(pmax, 0.f); mhat += d; alpha = FIRST ? 1.f : __builtin_amdgcn_exp2f(-d);
; #pragma unroll
;     for (int r = 0; r < 16; ++r) { p0[r] -= d; p1[r] -= d; }
; #pragma unroll
;     for (int r = 0; r < 16; ++r) negm[r] = -mhat; }
; #pragma unroll
;   for (int r = 0; r < 16; ++r) p0[r] = __builtin_amdgcn_exp2f(p0[r]);
; }
; __device__ __forceinline__ void finishSM(f32x16& p0, f32x16& p1, float alpha, float& l_reg, bf16x8& pa0, bf16x8& pa1, bf16x8& pa2, bf16x8& pa3) {
; #pragma unroll
;   for (int r = 0; r < 16; ++r) p1[r] = __builtin_amdgcn_exp2f(p1[r]);
;   float ps = 0;
; #pragma unroll
;   for (int r = 0; r < 16; ++r) ps += p0[r];
; #pragma unroll
;   for (int r = 0; r < 16; ++r) ps += p1[r];
;   { auto rr = __builtin_amdgcn_permlane32_swap(__float_as_uint(ps), __float_as_uint(ps), false, false);
;     ps = __uint_as_float(rr[0]) + __uint_as_float(rr[1]); }
;   l_reg = l_reg * alpha + ps;
;     ...
;   PK4(p0, 0, pa0); PK4(p0, 8, pa1); PK4(p1, 0, pa2); PK4(p1, 8, pa3);
;     ...
; }
; __device__ __forceinline__ void qkt(f32x16& p0, f32x16& p1, const bf16_t* Ks, const bf16x8* qr, const f32x16& negm, int r32, int hi) {
;   p0 = negm; p1 = negm;
; #pragma unroll
;   for (int d0 = 0; d0 < 6; ++d0) { int cb = (d0 * 16 + hi * 8) * 2;
;     bf16x8 b0 = *reinterpret_cast<const bf16x8*>((const char*)Ks + KSWZ(r32, cb));
;     bf16x8 b1 = *reinterpret_cast<const bf16x8*>((const char*)Ks + KSWZ(32 + r32, cb));
;     p0 = __builtin_amdgcn_mfma_f32_32x32x16_bf16(b0, qr[d0], p0, 0, 0, 0);
;     p1 = __builtin_amdgcn_mfma_f32_32x32x16_bf16(b1, qr[d0], p1, 0, 0, 0); }
; }
.Lat_loop:
	ds_read_b128 v[200:203], v142 offset:16384
	ds_read_b128 v[204:207], v142 offset:24576
	ds_read_b128 v[208:211], v143 offset:16384
	ds_read_b128 v[212:215], v143 offset:24576
	s_add_i32 m0, s6, 0
	s_mov_b64 exec, s[20:21]
	global_load_lds_dwordx4 v146, s[14:15]
	s_add_i32 m0, s6, 1024
	s_mov_b64 exec, s[22:23]
	global_load_lds_dwordx4 v147, s[14:15]
	s_add_i32 m0, s7, 32768
	s_mov_b64 exec, -1
	global_load_lds_dwordx4 v149, s[14:15]
	v_add_u32_e32 v146, v146, v148
	v_add_u32_e32 v147, v147, v217
	v_add_u32_e32 v149, 0x38000, v149
	s_waitcnt lgkmcnt(6)
	v_mfma_f32_32x32x16_bf16 v[66:81], v[184:187], v[114:117], v[98:113]
	ds_read_b128 v[184:187], v144 offset:16384
	v_exp_f32_e32 v50, v50
	v_exp_f32_e32 v51, v51
	v_exp_f32_e32 v52, v52
	v_exp_f32_e32 v53, v53
	v_exp_f32_e32 v54, v54
	v_mfma_f32_32x32x16_bf16 v[82:97], v[188:191], v[114:117], v[98:113]
	ds_read_b128 v[188:191], v144 offset:24576
	v_exp_f32_e32 v55, v55
	v_exp_f32_e32 v56, v56
	v_exp_f32_e32 v57, v57
	v_exp_f32_e32 v58, v58
	v_exp_f32_e32 v59, v59
	s_waitcnt lgkmcnt(6)
	v_mfma_f32_32x32x16_bf16 v[66:81], v[192:195], v[118:121], v[66:81]
	ds_read_b128 v[192:195], v145 offset:16384
	v_exp_f32_e32 v60, v60
	v_exp_f32_e32 v61, v61
	v_exp_f32_e32 v62, v62
	v_exp_f32_e32 v63, v63
	v_exp_f32_e32 v64, v64
	v_mfma_f32_32x32x16_bf16 v[82:97], v[196:199], v[118:121], v[82:97]
	ds_read_b128 v[196:199], v145 offset:24576
	v_exp_f32_e32 v65, v65
	v_cvt_pk_bf16_f32 v158, v34, v35
	v_cvt_pk_bf16_f32 v159, v36, v37
	v_cvt_pk_bf16_f32 v160, v38, v39
	v_cvt_pk_bf16_f32 v161, v40, v41
	s_waitcnt lgkmcnt(6)
	v_mfma_f32_32x32x16_bf16 v[66:81], v[200:203], v[122:125], v[66:81]
	ds_read_b64_tr_b16 v[200:201], v150 offset:8192
	ds_read_b64_tr_b16 v[202:203], v150 offset:10240
	v_cvt_pk_bf16_f32 v162, v42, v43
	v_cvt_pk_bf16_f32 v163, v44, v45
	v_cvt_pk_bf16_f32 v164, v46, v47
	v_cvt_pk_bf16_f32 v165, v48, v49
	v_add_f32_e32 v181, v181, v50
	v_mfma_f32_32x32x16_bf16 v[82:97], v[204:207], v[122:125], v[82:97]
	ds_read_b64_tr_b16 v[204:205], v150 offset:8704
	ds_read_b64_tr_b16 v[206:207], v150 offset:10752
	v_add_f32_e32 v182, v182, v51
	v_add_f32_e32 v183, v183, v52
	v_add_f32_e32 v216, v216, v53
	v_add_f32_e32 v181, v181, v54
	v_add_f32_e32 v182, v182, v55
	s_waitcnt lgkmcnt(8)
	v_mfma_f32_32x32x16_bf16 v[66:81], v[208:211], v[126:129], v[66:81]
	ds_read_b64_tr_b16 v[208:209], v150 offset:12288
	ds_read_b64_tr_b16 v[210:211], v150 offset:14336
	v_add_f32_e32 v183, v183, v56
	v_add_f32_e32 v216, v216, v57
	v_add_f32_e32 v181, v181, v58
	v_add_f32_e32 v182, v182, v59
	v_add_f32_e32 v183, v183, v60
	v_mfma_f32_32x32x16_bf16 v[82:97], v[212:215], v[126:129], v[82:97]
	ds_read_b64_tr_b16 v[212:213], v150 offset:12800
	ds_read_b64_tr_b16 v[214:215], v150 offset:14848
	v_add_f32_e32 v216, v216, v61
	v_add_f32_e32 v181, v181, v62
	v_add_f32_e32 v182, v182, v63
	v_add_f32_e32 v183, v183, v64
	v_add_f32_e32 v216, v216, v65
	s_waitcnt lgkmcnt(10)
	v_mfma_f32_32x32x16_bf16 v[66:81], v[184:187], v[130:133], v[66:81]
	ds_read_b64_tr_b16 v[184:185], v150 offset:0
	ds_read_b64_tr_b16 v[186:187], v150 offset:2048
	v_add_f32_e32 v181, v181, v182
	v_add_f32_e32 v183, v183, v216
	v_add_f32_e32 v181, v181, v183
	v_add_f32_e32 v174, v174, v181
	v_cvt_pk_bf16_f32 v166, v50, v51
	v_mfma_f32_32x32x16_bf16 v[82:97], v[188:191], v[130:133], v[82:97]
	ds_read_b64_tr_b16 v[188:189], v150 offset:512
	ds_read_b64_tr_b16 v[190:191], v150 offset:2560
	v_cvt_pk_bf16_f32 v167, v52, v53
	v_cvt_pk_bf16_f32 v168, v54, v55
	v_cvt_pk_bf16_f32 v169, v56, v57
	v_cvt_pk_bf16_f32 v170, v58, v59
	v_cvt_pk_bf16_f32 v171, v60, v61
	s_waitcnt lgkmcnt(12)
	v_mfma_f32_32x32x16_bf16 v[66:81], v[192:195], v[134:137], v[66:81]
	ds_read_b64_tr_b16 v[192:193], v150 offset:4096
	ds_read_b64_tr_b16 v[194:195], v150 offset:6144
	v_cvt_pk_bf16_f32 v172, v62, v63
	v_cvt_pk_bf16_f32 v173, v64, v65
	v_mfma_f32_32x32x16_bf16 v[82:97], v[196:199], v[134:137], v[82:97]
	ds_read_b64_tr_b16 v[196:197], v150 offset:4608
	s_waitcnt lgkmcnt(14)
	ds_read_b64_tr_b16 v[198:199], v150 offset:6656
	s_waitcnt lgkmcnt(4)
	v_mfma_f32_32x32x16_bf16 v[2:17], v[158:161], v[184:187], v[2:17]
	ds_read_b128 v[184:187], v140 offset:32768
	v_mfma_f32_32x32x16_bf16 v[18:33], v[158:161], v[188:191], v[18:33]
	ds_read_b128 v[188:191], v140 offset:40960
	v_max3_f32 v177, v66, v67, v68
	v_max3_f32 v178, v69, v70, v71
	v_max3_f32 v177, v177, v72, v73
	v_max3_f32 v178, v178, v74, v75
	v_max3_f32 v177, v177, v76, v77
	v_max3_f32 v178, v178, v78, v79
	v_max3_f32 v177, v177, v80, v81
	v_max3_f32 v178, v178, v82, v83
	s_waitcnt lgkmcnt(2)
	v_mfma_f32_32x32x16_bf16 v[2:17], v[162:165], v[192:195], v[2:17]
	ds_read_b128 v[192:195], v141 offset:32768
	v_max3_f32 v177, v177, v84, v85
	v_max3_f32 v178, v178, v86, v87
	v_max3_f32 v177, v177, v88, v89
	v_max3_f32 v178, v178, v90, v91
	v_max3_f32 v177, v177, v92, v93
	v_max3_f32 v178, v178, v94, v95
	v_max3_f32 v177, v177, v96, v97
	v_max_f32_e32 v177, v177, v178
	v_mfma_f32_32x32x16_bf16 v[18:33], v[162:165], v[196:199], v[18:33]
	ds_read_b128 v[196:199], v141 offset:40960
	v_cmp_ge_f32_e32 vcc, 0x4138aa3b, v177
	s_cmp_eq_u64 vcc, exec
	s_cbranch_scc0 .Lat_rare1_2

; template <bool FIRST> __device__ __forceinline__ void partialSM(f32x16& p0, f32x16& p1, float& mhat, f32x16& negm, float& alpha) {
;   float pa = fmaxf(fmaxf(p0[0], p0[1]), p1[0]), pb = fmaxf(fmaxf(p0[2], p0[3]), p1[1]); pa = fmaxf(fmaxf(pa, p1[2]), p1[3]);
; #pragma unroll
;   for (int r = 4; r < 16; r += 4) { pa = fmaxf(fmaxf(pa, p0[r]), p0[r + 1]); pb = fmaxf(fmaxf(pb, p0[r + 2]), p0[r + 3]); pa = fmaxf(fmaxf(pa, p1[r]), p1[r + 1]); pb = fmaxf(fmaxf(pb, p1[r + 2]), p1[r + 3]); }
;   float pmax = fmaxf(pa, pb);
;   { auto rr = __builtin_amdgcn_permlane32_swap(__float_as_uint(pmax), __float_as_uint(pmax), false, false);
;     pmax = fmaxf(__uint_as_float(rr[0]), __uint_as_float(rr[1])); }
;   if (!FIRST && __builtin_expect(__all(pmax <= THRL), 1)) { alpha = 1.f; }
;   else { const float d = FIRST ? pmax : fmaxf(pmax, 0.f); mhat += d; alpha = FIRST ? 1.f : __builtin_amdgcn_exp2f(-d);
; #pragma unroll
;     for (int r = 0; r < 16; ++r) { p0[r] -= d; p1[r] -= d; }
; #pragma unroll
;     for (int r = 0; r < 16; ++r) negm[r] = -mhat; }
; #pragma unroll
;   for (int r = 0; r < 16; ++r) p0[r] = __builtin_amdgcn_exp2f(p0[r]);
; }
; __device__ __forceinline__ void finishSM(f32x16& p0, f32x16& p1, float alpha, float& l_reg, bf16x8& pa0, bf16x8& pa1, bf16x8& pa2, bf16x8& pa3) {
; #pragma unroll
;   for (int r = 0; r < 16; ++r) p1[r] = __builtin_amdgcn_exp2f(p1[r]);
;   float ps = 0;
; #pragma unroll
;   for (int r = 0; r < 16; ++r) ps += p0[r];
; #pragma unroll
;   for (int r = 0; r < 16; ++r) ps += p1[r];
;   { auto rr = __builtin_amdgcn_permlane32_swap(__float_as_uint(ps), __float_as_uint(ps), false, false);
;     ps = __uint_as_float(rr[0]) + __uint_as_float(rr[1]); }
;   l_reg = l_reg * alpha + ps;
;     ...
;   PK4(p0, 0, pa0); PK4(p0, 8, pa1); PK4(p1, 0, pa2); PK4(p1, 8, pa3);
;     ...
; }
; __device__ __forceinline__ void qkt(f32x16& p0, f32x16& p1, const bf16_t* Ks, const bf16x8* qr, const f32x16& negm, int r32, int hi) {
;   p0 = negm; p1 = negm;
; #pragma unroll
;   for (int d0 = 0; d0 < 6; ++d0) { int cb = (d0 * 16 + hi * 8) * 2;
;     bf16x8 b0 = *reinterpret_cast<const bf16x8*>((const char*)Ks + KSWZ(r32, cb));
;     bf16x8 b1 = *reinterpret_cast<const bf16x8*>((const char*)Ks + KSWZ(32 + r32, cb));
;     p0 = __builtin_amdgcn_mfma_f32_32x32x16_bf16(b0, qr[d0], p0, 0, 0, 0);
;     p1 = __builtin_amdgcn_mfma_f32_32x32x16_bf16(b1, qr[d0], p1, 0, 0, 0); }
; }
.Lat_rr_4:
	s_waitcnt lgkmcnt(0)
	s_barrier
	ds_read_b128 v[200:203], v142 offset:32768
	ds_read_b128 v[204:207], v142 offset:40960
	ds_read_b128 v[208:211], v143 offset:32768
	ds_read_b128 v[212:215], v143 offset:40960
	s_add_i32 m0, s6, 16384
	s_mov_b64 exec, s[20:21]
	global_load_lds_dwordx4 v146, s[14:15]
	s_add_i32 m0, s6, 17408
	s_mov_b64 exec, s[22:23]
	global_load_lds_dwordx4 v147, s[14:15]
	s_add_i32 m0, s7, 49152
	s_mov_b64 exec, -1
	global_load_lds_dwordx4 v149, s[14:15]
	v_add_u32_e32 v146, v146, v148
	v_add_u32_e32 v147, v147, v217
	v_add_u32_e32 v149, 0x38000, v149
	v_mfma_f32_32x32x16_bf16 v[34:49], v[184:187], v[114:117], v[98:113]
	ds_read_b128 v[184:187], v144 offset:32768
	v_exp_f32_e32 v82, v82
	v_exp_f32_e32 v83, v83
	v_exp_f32_e32 v84, v84
	v_exp_f32_e32 v85, v85
	v_exp_f32_e32 v86, v86
	v_mfma_f32_32x32x16_bf16 v[50:65], v[188:191], v[114:117], v[98:113]
	ds_read_b128 v[188:191], v144 offset:40960
	v_exp_f32_e32 v87, v87
	v_exp_f32_e32 v88, v88
	v_exp_f32_e32 v89, v89
	v_exp_f32_e32 v90, v90
	v_exp_f32_e32 v91, v91
	v_mfma_f32_32x32x16_bf16 v[34:49], v[192:195], v[118:121], v[34:49]
	ds_read_b128 v[192:195], v145 offset:32768
	v_exp_f32_e32 v92, v92
	v_exp_f32_e32 v93, v93
	v_exp_f32_e32 v94, v94
	v_exp_f32_e32 v95, v95
	v_exp_f32_e32 v96, v96
	v_mfma_f32_32x32x16_bf16 v[50:65], v[196:199], v[118:121], v[50:65]
	ds_read_b128 v[196:199], v145 offset:40960
	v_exp_f32_e32 v97, v97
	v_cvt_pk_bf16_f32 v158, v66, v67
	v_cvt_pk_bf16_f32 v159, v68, v69
	v_cvt_pk_bf16_f32 v160, v70, v71
	v_cvt_pk_bf16_f32 v161, v72, v73
	s_waitcnt lgkmcnt(6)
	v_mfma_f32_32x32x16_bf16 v[34:49], v[200:203], v[122:125], v[34:49]
	ds_read_b64_tr_b16 v[200:201], v150 offset:24576
	ds_read_b64_tr_b16 v[202:203], v150 offset:26624
	v_cvt_pk_bf16_f32 v162, v74, v75
	v_cvt_pk_bf16_f32 v163, v76, v77
	v_cvt_pk_bf16_f32 v164, v78, v79
	v_cvt_pk_bf16_f32 v165, v80, v81
	v_add_f32_e32 v181, v181, v82
	v_mfma_f32_32x32x16_bf16 v[50:65], v[204:207], v[122:125], v[50:65]
	ds_read_b64_tr_b16 v[204:205], v150 offset:25088
	ds_read_b64_tr_b16 v[206:207], v150 offset:27136
	v_add_f32_e32 v182, v182, v83
	v_add_f32_e32 v183, v183, v84
	v_add_f32_e32 v216, v216, v85
	v_add_f32_e32 v181, v181, v86
	v_add_f32_e32 v182, v182, v87
	s_waitcnt lgkmcnt(8)
	v_mfma_f32_32x32x16_bf16 v[34:49], v[208:211], v[126:129], v[34:49]
	ds_read_b64_tr_b16 v[208:209], v150 offset:28672
	ds_read_b64_tr_b16 v[210:211], v150 offset:30720
	v_add_f32_e32 v183, v183, v88
	v_add_f32_e32 v216, v216, v89
	v_add_f32_e32 v181, v181, v90
	v_add_f32_e32 v182, v182, v91
	v_add_f32_e32 v183, v183, v92
	v_mfma_f32_32x32x16_bf16 v[50:65], v[212:215], v[126:129], v[50:65]
	ds_read_b64_tr_b16 v[212:213], v150 offset:29184
	ds_read_b64_tr_b16 v[214:215], v150 offset:31232
	v_add_f32_e32 v216, v216, v93
	v_add_f32_e32 v181, v181, v94
	v_add_f32_e32 v182, v182, v95
	v_add_f32_e32 v183, v183, v96
	v_add_f32_e32 v216, v216, v97
	s_waitcnt lgkmcnt(10)
	v_mfma_f32_32x32x16_bf16 v[34:49], v[184:187], v[130:133], v[34:49]
	ds_read_b64_tr_b16 v[184:185], v150 offset:16384
	ds_read_b64_tr_b16 v[186:187], v150 offset:18432
	v_add_f32_e32 v181, v181, v182
	v_add_f32_e32 v183, v183, v216
	v_add_f32_e32 v181, v181, v183
	v_add_f32_e32 v174, v174, v181
	v_cvt_pk_bf16_f32 v166, v82, v83
	v_mfma_f32_32x32x16_bf16 v[50:65], v[188:191], v[130:133], v[50:65]
	ds_read_b64_tr_b16 v[188:189], v150 offset:16896
	ds_read_b64_tr_b16 v[190:191], v150 offset:18944
	v_cvt_pk_bf16_f32 v167, v84, v85
	v_cvt_pk_bf16_f32 v168, v86, v87
	v_cvt_pk_bf16_f32 v169, v88, v89
	v_cvt_pk_bf16_f32 v170, v90, v91
	v_cvt_pk_bf16_f32 v171, v92, v93
	s_waitcnt lgkmcnt(12)
	v_mfma_f32_32x32x16_bf16 v[34:49], v[192:195], v[134:137], v[34:49]
	ds_read_b64_tr_b16 v[192:193], v150 offset:20480
	ds_read_b64_tr_b16 v[194:195], v150 offset:22528
	v_cvt_pk_bf16_f32 v172, v94, v95
	v_cvt_pk_bf16_f32 v173, v96, v97
	v_mfma_f32_32x32x16_bf16 v[50:65], v[196:199], v[134:137], v[50:65]
	ds_read_b64_tr_b16 v[196:197], v150 offset:20992
	s_waitcnt lgkmcnt(14)
	ds_read_b64_tr_b16 v[198:199], v150 offset:23040
	s_waitcnt lgkmcnt(4)
	v_mfma_f32_32x32x16_bf16 v[2:17], v[158:161], v[184:187], v[2:17]
	ds_read_b128 v[184:187], v140 offset:49152
	v_mfma_f32_32x32x16_bf16 v[18:33], v[158:161], v[188:191], v[18:33]
	ds_read_b128 v[188:191], v140 offset:57344
	v_max3_f32 v177, v34, v35, v36
	v_max3_f32 v178, v37, v38, v39
	v_max3_f32 v177, v177, v40, v41
	v_max3_f32 v178, v178, v42, v43
	v_max3_f32 v177, v177, v44, v45
	v_max3_f32 v178, v178, v46, v47
	v_max3_f32 v177, v177, v48, v49
	v_max3_f32 v178, v178, v50, v51
	s_waitcnt lgkmcnt(2)
	v_mfma_f32_32x32x16_bf16 v[2:17], v[162:165], v[192:195], v[2:17]
	ds_read_b128 v[192:195], v141 offset:49152
	v_max3_f32 v177, v177, v52, v53
	v_max3_f32 v178, v178, v54, v55
	v_max3_f32 v177, v177, v56, v57
	v_max3_f32 v178, v178, v58, v59
	v_max3_f32 v177, v177, v60, v61
	v_max3_f32 v178, v178, v62, v63
	v_max3_f32 v177, v177, v64, v65
	v_max_f32_e32 v177, v177, v178
	v_mfma_f32_32x32x16_bf16 v[18:33], v[162:165], v[196:199], v[18:33]
	ds_read_b128 v[196:199], v141 offset:57344
	v_cmp_ge_f32_e32 vcc, 0x4138aa3b, v177
	s_cmp_eq_u64 vcc, exec
	s_cbranch_scc0 .Lat_rare1_6

; template <bool FIRST> __device__ __forceinline__ void partialSM(f32x16& p0, f32x16& p1, float& mhat, f32x16& negm, float& alpha) {
;   float pa = fmaxf(fmaxf(p0[0], p0[1]), p1[0]), pb = fmaxf(fmaxf(p0[2], p0[3]), p1[1]); pa = fmaxf(fmaxf(pa, p1[2]), p1[3]);
; #pragma unroll
;   for (int r = 4; r < 16; r += 4) { pa = fmaxf(fmaxf(pa, p0[r]), p0[r + 1]); pb = fmaxf(fmaxf(pb, p0[r + 2]), p0[r + 3]); pa = fmaxf(fmaxf(pa, p1[r]), p1[r + 1]); pb = fmaxf(fmaxf(pb, p1[r + 2]), p1[r + 3]); }
;   float pmax = fmaxf(pa, pb);
;   { auto rr = __builtin_amdgcn_permlane32_swap(__float_as_uint(pmax), __float_as_uint(pmax), false, false);
;     pmax = fmaxf(__uint_as_float(rr[0]), __uint_as_float(rr[1])); }
;   if (!FIRST && __builtin_expect(__all(pmax <= THRL), 1)) { alpha = 1.f; }
;   else { const float d = FIRST ? pmax : fmaxf(pmax, 0.f); mhat += d; alpha = FIRST ? 1.f : __builtin_amdgcn_exp2f(-d);
; #pragma unroll
;     for (int r = 0; r < 16; ++r) { p0[r] -= d; p1[r] -= d; }
; #pragma unroll
;     for (int r = 0; r < 16; ++r) negm[r] = -mhat; }
; #pragma unroll
;   for (int r = 0; r < 16; ++r) p0[r] = __builtin_amdgcn_exp2f(p0[r]);
; }
; __device__ __forceinline__ void finishSM(f32x16& p0, f32x16& p1, float alpha, float& l_reg, bf16x8& pa0, bf16x8& pa1, bf16x8& pa2, bf16x8& pa3) {
; #pragma unroll
;   for (int r = 0; r < 16; ++r) p1[r] = __builtin_amdgcn_exp2f(p1[r]);
;   float ps = 0;
; #pragma unroll
;   for (int r = 0; r < 16; ++r) ps += p0[r];
; #pragma unroll
;   for (int r = 0; r < 16; ++r) ps += p1[r];
;   { auto rr = __builtin_amdgcn_permlane32_swap(__float_as_uint(ps), __float_as_uint(ps), false, false);
;     ps = __uint_as_float(rr[0]) + __uint_as_float(rr[1]); }
;   l_reg = l_reg * alpha + ps;
;     ...
;   PK4(p0, 0, pa0); PK4(p0, 8, pa1); PK4(p1, 0, pa2); PK4(p1, 8, pa3);
;     ...
; }
; __device__ __forceinline__ void qkt(f32x16& p0, f32x16& p1, const bf16_t* Ks, const bf16x8* qr, const f32x16& negm, int r32, int hi) {
;   p0 = negm; p1 = negm;
; #pragma unroll
;   for (int d0 = 0; d0 < 6; ++d0) { int cb = (d0 * 16 + hi * 8) * 2;
;     bf16x8 b0 = *reinterpret_cast<const bf16x8*>((const char*)Ks + KSWZ(r32, cb));
;     bf16x8 b1 = *reinterpret_cast<const bf16x8*>((const char*)Ks + KSWZ(32 + r32, cb));
;     p0 = __builtin_amdgcn_mfma_f32_32x32x16_bf16(b0, qr[d0], p0, 0, 0, 0);
;     p1 = __builtin_amdgcn_mfma_f32_32x32x16_bf16(b1, qr[d0], p1, 0, 0, 0); }
; }
.Lat_rr_8:
	s_waitcnt lgkmcnt(0)
	s_barrier
	ds_read_b128 v[200:203], v142 offset:49152
	ds_read_b128 v[204:207], v142 offset:57344
	ds_read_b128 v[208:211], v143 offset:49152
	ds_read_b128 v[212:215], v143 offset:57344
	s_add_i32 m0, s6, 32768
	s_mov_b64 exec, s[20:21]
	global_load_lds_dwordx4 v146, s[14:15]
	s_add_i32 m0, s6, 33792
	s_mov_b64 exec, s[22:23]
	global_load_lds_dwordx4 v147, s[14:15]
	s_add_i32 m0, s7, 0
	s_mov_b64 exec, -1
	global_load_lds_dwordx4 v149, s[14:15]
	v_add_u32_e32 v146, v146, v148
	v_add_u32_e32 v147, v147, v217
	v_add_u32_e32 v149, 0x38000, v149
	v_mfma_f32_32x32x16_bf16 v[66:81], v[184:187], v[114:117], v[98:113]
	ds_read_b128 v[184:187], v144 offset:49152
	v_exp_f32_e32 v50, v50
	v_exp_f32_e32 v51, v51
	v_exp_f32_e32 v52, v52
	v_exp_f32_e32 v53, v53
	v_exp_f32_e32 v54, v54
	v_mfma_f32_32x32x16_bf16 v[82:97], v[188:191], v[114:117], v[98:113]
	ds_read_b128 v[188:191], v144 offset:57344
	v_exp_f32_e32 v55, v55
	v_exp_f32_e32 v56, v56
	v_exp_f32_e32 v57, v57
	v_exp_f32_e32 v58, v58
	v_exp_f32_e32 v59, v59
	v_mfma_f32_32x32x16_bf16 v[66:81], v[192:195], v[118:121], v[66:81]
	ds_read_b128 v[192:195], v145 offset:49152
	v_exp_f32_e32 v60, v60
	v_exp_f32_e32 v61, v61
	v_exp_f32_e32 v62, v62
	v_exp_f32_e32 v63, v63
	v_exp_f32_e32 v64, v64
	v_mfma_f32_32x32x16_bf16 v[82:97], v[196:199], v[118:121], v[82:97]
	ds_read_b128 v[196:199], v145 offset:57344
	v_exp_f32_e32 v65, v65
	v_cvt_pk_bf16_f32 v158, v34, v35
	v_cvt_pk_bf16_f32 v159, v36, v37
	v_cvt_pk_bf16_f32 v160, v38, v39
	v_cvt_pk_bf16_f32 v161, v40, v41
	s_waitcnt lgkmcnt(6)
	v_mfma_f32_32x32x16_bf16 v[66:81], v[200:203], v[122:125], v[66:81]
	ds_read_b64_tr_b16 v[200:201], v150 offset:40960
	ds_read_b64_tr_b16 v[202:203], v150 offset:43008
	v_cvt_pk_bf16_f32 v162, v42, v43
	v_cvt_pk_bf16_f32 v163, v44, v45
	v_cvt_pk_bf16_f32 v164, v46, v47
	v_cvt_pk_bf16_f32 v165, v48, v49
	v_add_f32_e32 v181, v181, v50
	v_mfma_f32_32x32x16_bf16 v[82:97], v[204:207], v[122:125], v[82:97]
	ds_read_b64_tr_b16 v[204:205], v150 offset:41472
	ds_read_b64_tr_b16 v[206:207], v150 offset:43520
	v_add_f32_e32 v182, v182, v51
	v_add_f32_e32 v183, v183, v52
	v_add_f32_e32 v216, v216, v53
	v_add_f32_e32 v181, v181, v54
	v_add_f32_e32 v182, v182, v55
	s_waitcnt lgkmcnt(8)
	v_mfma_f32_32x32x16_bf16 v[66:81], v[208:211], v[126:129], v[66:81]
	ds_read_b64_tr_b16 v[208:209], v150 offset:45056
	ds_read_b64_tr_b16 v[210:211], v150 offset:47104
	v_add_f32_e32 v183, v183, v56
	v_add_f32_e32 v216, v216, v57
	v_add_f32_e32 v181, v181, v58
	v_add_f32_e32 v182, v182, v59
	v_add_f32_e32 v183, v183, v60
	v_mfma_f32_32x32x16_bf16 v[82:97], v[212:215], v[126:129], v[82:97]
	ds_read_b64_tr_b16 v[212:213], v150 offset:45568
	ds_read_b64_tr_b16 v[214:215], v150 offset:47616
	v_add_f32_e32 v216, v216, v61
	v_add_f32_e32 v181, v181, v62
	v_add_f32_e32 v182, v182, v63
	v_add_f32_e32 v183, v183, v64
	v_add_f32_e32 v216, v216, v65
	s_waitcnt lgkmcnt(10)
	v_mfma_f32_32x32x16_bf16 v[66:81], v[184:187], v[130:133], v[66:81]
	ds_read_b64_tr_b16 v[184:185], v150 offset:32768
	ds_read_b64_tr_b16 v[186:187], v150 offset:34816
	v_add_f32_e32 v181, v181, v182
	v_add_f32_e32 v183, v183, v216
	v_add_f32_e32 v181, v181, v183
	v_add_f32_e32 v174, v174, v181
	v_cvt_pk_bf16_f32 v166, v50, v51
	v_mfma_f32_32x32x16_bf16 v[82:97], v[188:191], v[130:133], v[82:97]
	ds_read_b64_tr_b16 v[188:189], v150 offset:33280
	ds_read_b64_tr_b16 v[190:191], v150 offset:35328
	v_cvt_pk_bf16_f32 v167, v52, v53
	v_cvt_pk_bf16_f32 v168, v54, v55
	v_cvt_pk_bf16_f32 v169, v56, v57
	v_cvt_pk_bf16_f32 v170, v58, v59
	v_cvt_pk_bf16_f32 v171, v60, v61
	s_waitcnt lgkmcnt(12)
	v_mfma_f32_32x32x16_bf16 v[66:81], v[192:195], v[134:137], v[66:81]
	ds_read_b64_tr_b16 v[192:193], v150 offset:36864
	ds_read_b64_tr_b16 v[194:195], v150 offset:38912
	v_cvt_pk_bf16_f32 v172, v62, v63
	v_cvt_pk_bf16_f32 v173, v64, v65
	v_mfma_f32_32x32x16_bf16 v[82:97], v[196:199], v[134:137], v[82:97]
	ds_read_b64_tr_b16 v[196:197], v150 offset:37376
	s_waitcnt lgkmcnt(14)
	ds_read_b64_tr_b16 v[198:199], v150 offset:39424
	s_waitcnt lgkmcnt(4)
	v_mfma_f32_32x32x16_bf16 v[2:17], v[158:161], v[184:187], v[2:17]
	ds_read_b128 v[184:187], v140 offset:0
	v_mfma_f32_32x32x16_bf16 v[18:33], v[158:161], v[188:191], v[18:33]
	ds_read_b128 v[188:191], v140 offset:8192
	v_max3_f32 v177, v66, v67, v68
	v_max3_f32 v178, v69, v70, v71
	v_max3_f32 v177, v177, v72, v73
	v_max3_f32 v178, v178, v74, v75
	v_max3_f32 v177, v177, v76, v77
	v_max3_f32 v178, v178, v78, v79
	v_max3_f32 v177, v177, v80, v81
	v_max3_f32 v178, v178, v82, v83
	s_waitcnt lgkmcnt(2)
	v_mfma_f32_32x32x16_bf16 v[2:17], v[162:165], v[192:195], v[2:17]
	ds_read_b128 v[192:195], v141 offset:0
	v_max3_f32 v177, v177, v84, v85
	v_max3_f32 v178, v178, v86, v87
	v_max3_f32 v177, v177, v88, v89
	v_max3_f32 v178, v178, v90, v91
	v_max3_f32 v177, v177, v92, v93
	v_max3_f32 v178, v178, v94, v95
	v_max3_f32 v177, v177, v96, v97
	v_max_f32_e32 v177, v177, v178
	v_mfma_f32_32x32x16_bf16 v[18:33], v[162:165], v[196:199], v[18:33]
	ds_read_b128 v[196:199], v141 offset:8192
	v_cmp_ge_f32_e32 vcc, 0x4138aa3b, v177
	s_cmp_eq_u64 vcc, exec
	s_cbranch_scc0 .Lat_rare1_10

; template <bool FIRST> __device__ __forceinline__ void partialSM(f32x16& p0, f32x16& p1, float& mhat, f32x16& negm, float& alpha) {
;   float pa = fmaxf(fmaxf(p0[0], p0[1]), p1[0]), pb = fmaxf(fmaxf(p0[2], p0[3]), p1[1]); pa = fmaxf(fmaxf(pa, p1[2]), p1[3]);
; #pragma unroll
;   for (int r = 4; r < 16; r += 4) { pa = fmaxf(fmaxf(pa, p0[r]), p0[r + 1]); pb = fmaxf(fmaxf(pb, p0[r + 2]), p0[r + 3]); pa = fmaxf(fmaxf(pa, p1[r]), p1[r + 1]); pb = fmaxf(fmaxf(pb, p1[r + 2]), p1[r + 3]); }
;   float pmax = fmaxf(pa, pb);
;   { auto rr = __builtin_amdgcn_permlane32_swap(__float_as_uint(pmax), __float_as_uint(pmax), false, false);
;     pmax = fmaxf(__uint_as_float(rr[0]), __uint_as_float(rr[1])); }
;   if (!FIRST && __builtin_expect(__all(pmax <= THRL), 1)) { alpha = 1.f; }
;   else { const float d = FIRST ? pmax : fmaxf(pmax, 0.f); mhat += d; alpha = FIRST ? 1.f : __builtin_amdgcn_exp2f(-d);
; #pragma unroll
;     for (int r = 0; r < 16; ++r) { p0[r] -= d; p1[r] -= d; }
; #pragma unroll
;     for (int r = 0; r < 16; ++r) negm[r] = -mhat; }
; #pragma unroll
;   for (int r = 0; r < 16; ++r) p0[r] = __builtin_amdgcn_exp2f(p0[r]);
; }
; __device__ __forceinline__ void finishSM(f32x16& p0, f32x16& p1, float alpha, float& l_reg, bf16x8& pa0, bf16x8& pa1, bf16x8& pa2, bf16x8& pa3) {
; #pragma unroll
;   for (int r = 0; r < 16; ++r) p1[r] = __builtin_amdgcn_exp2f(p1[r]);
;   float ps = 0;
; #pragma unroll
;   for (int r = 0; r < 16; ++r) ps += p0[r];
; #pragma unroll
;   for (int r = 0; r < 16; ++r) ps += p1[r];
;   { auto rr = __builtin_amdgcn_permlane32_swap(__float_as_uint(ps), __float_as_uint(ps), false, false);
;     ps = __uint_as_float(rr[0]) + __uint_as_float(rr[1]); }
;   l_reg = l_reg * alpha + ps;
;     ...
;   PK4(p0, 0, pa0); PK4(p0, 8, pa1); PK4(p1, 0, pa2); PK4(p1, 8, pa3);
;     ...
; }
; __device__ __forceinline__ void qkt(f32x16& p0, f32x16& p1, const bf16_t* Ks, const bf16x8* qr, const f32x16& negm, int r32, int hi) {
;   p0 = negm; p1 = negm;
; #pragma unroll
;   for (int d0 = 0; d0 < 6; ++d0) { int cb = (d0 * 16 + hi * 8) * 2;
;     bf16x8 b0 = *reinterpret_cast<const bf16x8*>((const char*)Ks + KSWZ(r32, cb));
;     bf16x8 b1 = *reinterpret_cast<const bf16x8*>((const char*)Ks + KSWZ(32 + r32, cb));
;     p0 = __builtin_amdgcn_mfma_f32_32x32x16_bf16(b0, qr[d0], p0, 0, 0, 0);
;     p1 = __builtin_amdgcn_mfma_f32_32x32x16_bf16(b1, qr[d0], p1, 0, 0, 0); }
; }
.Lat_rr_12:
	s_waitcnt lgkmcnt(0)
	s_barrier
	ds_read_b128 v[200:203], v142 offset:0
	ds_read_b128 v[204:207], v142 offset:8192
	ds_read_b128 v[208:211], v143 offset:0
	ds_read_b128 v[212:215], v143 offset:8192
	s_add_i32 m0, s6, 49152
	s_mov_b64 exec, s[20:21]
	global_load_lds_dwordx4 v146, s[14:15]
	s_add_i32 m0, s6, 50176
	s_mov_b64 exec, s[22:23]
	global_load_lds_dwordx4 v147, s[14:15]
	s_add_i32 m0, s7, 16384
	s_mov_b64 exec, -1
	global_load_lds_dwordx4 v149, s[14:15]
	v_add_u32_e32 v146, v146, v148
	v_add_u32_e32 v147, v147, v217
	v_add_u32_e32 v149, 0x38000, v149
	v_mfma_f32_32x32x16_bf16 v[34:49], v[184:187], v[114:117], v[98:113]
	ds_read_b128 v[184:187], v144 offset:0
	v_exp_f32_e32 v82, v82
	v_exp_f32_e32 v83, v83
	v_exp_f32_e32 v84, v84
	v_exp_f32_e32 v85, v85
	v_exp_f32_e32 v86, v86
	v_mfma_f32_32x32x16_bf16 v[50:65], v[188:191], v[114:117], v[98:113]
	ds_read_b128 v[188:191], v144 offset:8192
	v_exp_f32_e32 v87, v87
	v_exp_f32_e32 v88, v88
	v_exp_f32_e32 v89, v89
	v_exp_f32_e32 v90, v90
	v_exp_f32_e32 v91, v91
	v_mfma_f32_32x32x16_bf16 v[34:49], v[192:195], v[118:121], v[34:49]
	ds_read_b128 v[192:195], v145 offset:0
	v_exp_f32_e32 v92, v92
	v_exp_f32_e32 v93, v93
	v_exp_f32_e32 v94, v94
	v_exp_f32_e32 v95, v95
	v_exp_f32_e32 v96, v96
	v_mfma_f32_32x32x16_bf16 v[50:65], v[196:199], v[118:121], v[50:65]
	ds_read_b128 v[196:199], v145 offset:8192
	v_exp_f32_e32 v97, v97
	v_cvt_pk_bf16_f32 v158, v66, v67
	v_cvt_pk_bf16_f32 v159, v68, v69
	v_cvt_pk_bf16_f32 v160, v70, v71
	v_cvt_pk_bf16_f32 v161, v72, v73
	s_waitcnt lgkmcnt(6)
	v_mfma_f32_32x32x16_bf16 v[34:49], v[200:203], v[122:125], v[34:49]
	ds_read_b64_tr_b16 v[200:201], v150 offset:57344
	ds_read_b64_tr_b16 v[202:203], v150 offset:59392
	v_cvt_pk_bf16_f32 v162, v74, v75
	v_cvt_pk_bf16_f32 v163, v76, v77
	v_cvt_pk_bf16_f32 v164, v78, v79
	v_cvt_pk_bf16_f32 v165, v80, v81
	v_add_f32_e32 v181, v181, v82
	v_mfma_f32_32x32x16_bf16 v[50:65], v[204:207], v[122:125], v[50:65]
	ds_read_b64_tr_b16 v[204:205], v150 offset:57856
	ds_read_b64_tr_b16 v[206:207], v150 offset:59904
	v_add_f32_e32 v182, v182, v83
	v_add_f32_e32 v183, v183, v84
	v_add_f32_e32 v216, v216, v85
	v_add_f32_e32 v181, v181, v86
	v_add_f32_e32 v182, v182, v87
	s_waitcnt lgkmcnt(8)
	v_mfma_f32_32x32x16_bf16 v[34:49], v[208:211], v[126:129], v[34:49]
	ds_read_b64_tr_b16 v[208:209], v150 offset:61440
	ds_read_b64_tr_b16 v[210:211], v150 offset:63488
	v_add_f32_e32 v183, v183, v88
	v_add_f32_e32 v216, v216, v89
	v_add_f32_e32 v181, v181, v90
	v_add_f32_e32 v182, v182, v91
	v_add_f32_e32 v183, v183, v92
	v_mfma_f32_32x32x16_bf16 v[50:65], v[212:215], v[126:129], v[50:65]
	ds_read_b64_tr_b16 v[212:213], v150 offset:61952
	ds_read_b64_tr_b16 v[214:215], v150 offset:64000
	v_add_f32_e32 v216, v216, v93
	v_add_f32_e32 v181, v181, v94
	v_add_f32_e32 v182, v182, v95
	v_add_f32_e32 v183, v183, v96
	v_add_f32_e32 v216, v216, v97
	s_waitcnt lgkmcnt(10)
	v_mfma_f32_32x32x16_bf16 v[34:49], v[184:187], v[130:133], v[34:49]
	ds_read_b64_tr_b16 v[184:185], v150 offset:49152
	ds_read_b64_tr_b16 v[186:187], v150 offset:51200
	v_add_f32_e32 v181, v181, v182
	v_add_f32_e32 v183, v183, v216
	v_add_f32_e32 v181, v181, v183
	v_add_f32_e32 v174, v174, v181
	v_cvt_pk_bf16_f32 v166, v82, v83
	v_mfma_f32_32x32x16_bf16 v[50:65], v[188:191], v[130:133], v[50:65]
	ds_read_b64_tr_b16 v[188:189], v150 offset:49664
	ds_read_b64_tr_b16 v[190:191], v150 offset:51712
	v_cvt_pk_bf16_f32 v167, v84, v85
	v_cvt_pk_bf16_f32 v168, v86, v87
	v_cvt_pk_bf16_f32 v169, v88, v89
	v_cvt_pk_bf16_f32 v170, v90, v91
	v_cvt_pk_bf16_f32 v171, v92, v93
	s_waitcnt lgkmcnt(12)
	v_mfma_f32_32x32x16_bf16 v[34:49], v[192:195], v[134:137], v[34:49]
	ds_read_b64_tr_b16 v[192:193], v150 offset:53248
	ds_read_b64_tr_b16 v[194:195], v150 offset:55296
	v_cvt_pk_bf16_f32 v172, v94, v95
	v_cvt_pk_bf16_f32 v173, v96, v97
	v_mfma_f32_32x32x16_bf16 v[50:65], v[196:199], v[134:137], v[50:65]
	ds_read_b64_tr_b16 v[196:197], v150 offset:53760
	s_waitcnt lgkmcnt(14)
	ds_read_b64_tr_b16 v[198:199], v150 offset:55808
	s_waitcnt lgkmcnt(4)
	v_mfma_f32_32x32x16_bf16 v[2:17], v[158:161], v[184:187], v[2:17]
	ds_read_b128 v[184:187], v140 offset:16384
	v_mfma_f32_32x32x16_bf16 v[18:33], v[158:161], v[188:191], v[18:33]
	ds_read_b128 v[188:191], v140 offset:24576
	v_max3_f32 v177, v34, v35, v36
	v_max3_f32 v178, v37, v38, v39
	v_max3_f32 v177, v177, v40, v41
	v_max3_f32 v178, v178, v42, v43
	v_max3_f32 v177, v177, v44, v45
	v_max3_f32 v178, v178, v46, v47
	v_max3_f32 v177, v177, v48, v49
	v_max3_f32 v178, v178, v50, v51
	s_waitcnt lgkmcnt(2)
	v_mfma_f32_32x32x16_bf16 v[2:17], v[162:165], v[192:195], v[2:17]
	ds_read_b128 v[192:195], v141 offset:16384
	v_max3_f32 v177, v177, v52, v53
	v_max3_f32 v178, v178, v54, v55
	v_max3_f32 v177, v177, v56, v57
	v_max3_f32 v178, v178, v58, v59
	v_max3_f32 v177, v177, v60, v61
	v_max3_f32 v178, v178, v62, v63
	v_max3_f32 v177, v177, v64, v65
	v_max_f32_e32 v177, v177, v178
	v_mfma_f32_32x32x16_bf16 v[18:33], v[162:165], v[196:199], v[18:33]
	ds_read_b128 v[196:199], v141 offset:24576
	v_cmp_ge_f32_e32 vcc, 0x4138aa3b, v177
	s_cmp_eq_u64 vcc, exec
	s_cbranch_scc0 .Lat_rare1_14

; template <bool FIRST> __device__ __forceinline__ void partialSM(f32x16& p0, f32x16& p1, float& mhat, f32x16& negm, float& alpha) {
;   float pa = fmaxf(fmaxf(p0[0], p0[1]), p1[0]), pb = fmaxf(fmaxf(p0[2], p0[3]), p1[1]); pa = fmaxf(fmaxf(pa, p1[2]), p1[3]);
; #pragma unroll
;   for (int r = 4; r < 16; r += 4) { pa = fmaxf(fmaxf(pa, p0[r]), p0[r + 1]); pb = fmaxf(fmaxf(pb, p0[r + 2]), p0[r + 3]); pa = fmaxf(fmaxf(pa, p1[r]), p1[r + 1]); pb = fmaxf(fmaxf(pb, p1[r + 2]), p1[r + 3]); }
;   float pmax = fmaxf(pa, pb);
;   { auto rr = __builtin_amdgcn_permlane32_swap(__float_as_uint(pmax), __float_as_uint(pmax), false, false);
;     pmax = fmaxf(__uint_as_float(rr[0]), __uint_as_float(rr[1])); }
;   if (!FIRST && __builtin_expect(__all(pmax <= THRL), 1)) { alpha = 1.f; }
;   else { const float d = FIRST ? pmax : fmaxf(pmax, 0.f); mhat += d; alpha = FIRST ? 1.f : __builtin_amdgcn_exp2f(-d);
; #pragma unroll
;     for (int r = 0; r < 16; ++r) { p0[r] -= d; p1[r] -= d; }
; #pragma unroll
;     for (int r = 0; r < 16; ++r) negm[r] = -mhat; }
; #pragma unroll
;   for (int r = 0; r < 16; ++r) p0[r] = __builtin_amdgcn_exp2f(p0[r]);
; }
; __device__ __forceinline__ void finishSM(f32x16& p0, f32x16& p1, float alpha, float& l_reg, bf16x8& pa0, bf16x8& pa1, bf16x8& pa2, bf16x8& pa3) {
; #pragma unroll
;   for (int r = 0; r < 16; ++r) p1[r] = __builtin_amdgcn_exp2f(p1[r]);
;   float ps = 0;
; #pragma unroll
;   for (int r = 0; r < 16; ++r) ps += p0[r];
; #pragma unroll
;   for (int r = 0; r < 16; ++r) ps += p1[r];
;   { auto rr = __builtin_amdgcn_permlane32_swap(__float_as_uint(ps), __float_as_uint(ps), false, false);
;     ps = __uint_as_float(rr[0]) + __uint_as_float(rr[1]); }
;   l_reg = l_reg * alpha + ps;
;     ...
;   PK4(p0, 0, pa0); PK4(p0, 8, pa1); PK4(p1, 0, pa2); PK4(p1, 8, pa3);
;     ...
; }
; __device__ __forceinline__ void qkt(f32x16& p0, f32x16& p1, const bf16_t* Ks, const bf16x8* qr, const f32x16& negm, int r32, int hi) {
;   p0 = negm; p1 = negm;
; #pragma unroll
;   for (int d0 = 0; d0 < 6; ++d0) { int cb = (d0 * 16 + hi * 8) * 2;
;     bf16x8 b0 = *reinterpret_cast<const bf16x8*>((const char*)Ks + KSWZ(r32, cb));
;     bf16x8 b1 = *reinterpret_cast<const bf16x8*>((const char*)Ks + KSWZ(32 + r32, cb));
;     p0 = __builtin_amdgcn_mfma_f32_32x32x16_bf16(b0, qr[d0], p0, 0, 0, 0);
;     p1 = __builtin_amdgcn_mfma_f32_32x32x16_bf16(b1, qr[d0], p1, 0, 0, 0); }
; }
.Lat_rr_16:
	s_waitcnt lgkmcnt(0)
	s_barrier
	s_add_i32 s8, s8, 1
	s_cmp_lt_u32 s8, 31
	s_cbranch_scc1 .Lat_loop
	ds_read_b128 v[200:203], v142 offset:16384
	ds_read_b128 v[204:207], v142 offset:24576
	ds_read_b128 v[208:211], v143 offset:16384
	ds_read_b128 v[212:215], v143 offset:24576
	s_add_i32 m0, s7, 32768
	s_mov_b64 exec, -1
	global_load_lds_dwordx4 v149, s[14:15]
	v_add_u32_e32 v149, 0x38000, v149
	v_mfma_f32_32x32x16_bf16 v[66:81], v[184:187], v[114:117], v[98:113]
	ds_read_b128 v[184:187], v144 offset:16384
	v_exp_f32_e32 v50, v50
	v_exp_f32_e32 v51, v51
	v_exp_f32_e32 v52, v52
	v_exp_f32_e32 v53, v53
	v_exp_f32_e32 v54, v54
	v_mfma_f32_32x32x16_bf16 v[82:97], v[188:191], v[114:117], v[98:113]
	ds_read_b128 v[188:191], v144 offset:24576
	v_exp_f32_e32 v55, v55
	v_exp_f32_e32 v56, v56
	v_exp_f32_e32 v57, v57
	v_exp_f32_e32 v58, v58
	v_exp_f32_e32 v59, v59
	v_mfma_f32_32x32x16_bf16 v[66:81], v[192:195], v[118:121], v[66:81]
	ds_read_b128 v[192:195], v145 offset:16384
	v_exp_f32_e32 v60, v60
	v_exp_f32_e32 v61, v61
	v_exp_f32_e32 v62, v62
	v_exp_f32_e32 v63, v63
	v_exp_f32_e32 v64, v64
	v_mfma_f32_32x32x16_bf16 v[82:97], v[196:199], v[118:121], v[82:97]
	ds_read_b128 v[196:199], v145 offset:24576
	v_exp_f32_e32 v65, v65
	v_cvt_pk_bf16_f32 v158, v34, v35
	v_cvt_pk_bf16_f32 v159, v36, v37
	v_cvt_pk_bf16_f32 v160, v38, v39
	v_cvt_pk_bf16_f32 v161, v40, v41
	s_waitcnt lgkmcnt(6)
	v_mfma_f32_32x32x16_bf16 v[66:81], v[200:203], v[122:125], v[66:81]
	ds_read_b64_tr_b16 v[200:201], v150 offset:8192
	ds_read_b64_tr_b16 v[202:203], v150 offset:10240
	v_cvt_pk_bf16_f32 v162, v42, v43
	v_cvt_pk_bf16_f32 v163, v44, v45
	v_cvt_pk_bf16_f32 v164, v46, v47
	v_cvt_pk_bf16_f32 v165, v48, v49
	v_add_f32_e32 v181, v181, v50
	v_mfma_f32_32x32x16_bf16 v[82:97], v[204:207], v[122:125], v[82:97]
	ds_read_b64_tr_b16 v[204:205], v150 offset:8704
	ds_read_b64_tr_b16 v[206:207], v150 offset:10752
	v_add_f32_e32 v182, v182, v51
	v_add_f32_e32 v183, v183, v52
	v_add_f32_e32 v216, v216, v53
	v_add_f32_e32 v181, v181, v54
	v_add_f32_e32 v182, v182, v55
	s_waitcnt lgkmcnt(8)
	v_mfma_f32_32x32x16_bf16 v[66:81], v[208:211], v[126:129], v[66:81]
	ds_read_b64_tr_b16 v[208:209], v150 offset:12288
	ds_read_b64_tr_b16 v[210:211], v150 offset:14336
	v_add_f32_e32 v183, v183, v56
	v_add_f32_e32 v216, v216, v57
	v_add_f32_e32 v181, v181, v58
	v_add_f32_e32 v182, v182, v59
	v_add_f32_e32 v183, v183, v60
	v_mfma_f32_32x32x16_bf16 v[82:97], v[212:215], v[126:129], v[82:97]
	ds_read_b64_tr_b16 v[212:213], v150 offset:12800
	ds_read_b64_tr_b16 v[214:215], v150 offset:14848
	v_add_f32_e32 v216, v216, v61
	v_add_f32_e32 v181, v181, v62
	v_add_f32_e32 v182, v182, v63
	v_add_f32_e32 v183, v183, v64
	v_add_f32_e32 v216, v216, v65
	s_waitcnt lgkmcnt(10)
	v_mfma_f32_32x32x16_bf16 v[66:81], v[184:187], v[130:133], v[66:81]
	ds_read_b64_tr_b16 v[184:185], v150 offset:0
	ds_read_b64_tr_b16 v[186:187], v150 offset:2048
	v_add_f32_e32 v181, v181, v182
	v_add_f32_e32 v183, v183, v216
	v_add_f32_e32 v181, v181, v183
	v_add_f32_e32 v174, v174, v181
	v_cvt_pk_bf16_f32 v166, v50, v51
	v_mfma_f32_32x32x16_bf16 v[82:97], v[188:191], v[130:133], v[82:97]
	ds_read_b64_tr_b16 v[188:189], v150 offset:512
	ds_read_b64_tr_b16 v[190:191], v150 offset:2560
	v_cvt_pk_bf16_f32 v167, v52, v53
	v_cvt_pk_bf16_f32 v168, v54, v55
	v_cvt_pk_bf16_f32 v169, v56, v57
	v_cvt_pk_bf16_f32 v170, v58, v59
	v_cvt_pk_bf16_f32 v171, v60, v61
	s_waitcnt lgkmcnt(12)
	v_mfma_f32_32x32x16_bf16 v[66:81], v[192:195], v[134:137], v[66:81]
	ds_read_b64_tr_b16 v[192:193], v150 offset:4096
	ds_read_b64_tr_b16 v[194:195], v150 offset:6144
	v_cvt_pk_bf16_f32 v172, v62, v63
	v_cvt_pk_bf16_f32 v173, v64, v65
	v_mfma_f32_32x32x16_bf16 v[82:97], v[196:199], v[134:137], v[82:97]
	ds_read_b64_tr_b16 v[196:197], v150 offset:4608
	s_waitcnt lgkmcnt(14)
	ds_read_b64_tr_b16 v[198:199], v150 offset:6656
	s_waitcnt lgkmcnt(4)
	v_mfma_f32_32x32x16_bf16 v[2:17], v[158:161], v[184:187], v[2:17]
	ds_read_b128 v[184:187], v140 offset:32768
	v_mfma_f32_32x32x16_bf16 v[18:33], v[158:161], v[188:191], v[18:33]
	ds_read_b128 v[188:191], v140 offset:40960
	v_max3_f32 v177, v66, v67, v68
	v_max3_f32 v178, v69, v70, v71
	v_max3_f32 v177, v177, v72, v73
	v_max3_f32 v178, v178, v74, v75
	v_max3_f32 v177, v177, v76, v77
	v_max3_f32 v178, v178, v78, v79
	v_max3_f32 v177, v177, v80, v81
	v_max3_f32 v178, v178, v82, v83
	s_waitcnt lgkmcnt(2)
	v_mfma_f32_32x32x16_bf16 v[2:17], v[162:165], v[192:195], v[2:17]
	ds_read_b128 v[192:195], v141 offset:32768
	v_max3_f32 v177, v177, v84, v85
	v_max3_f32 v178, v178, v86, v87
	v_max3_f32 v177, v177, v88, v89
	v_max3_f32 v178, v178, v90, v91
	v_max3_f32 v177, v177, v92, v93
	v_max3_f32 v178, v178, v94, v95
	v_max3_f32 v177, v177, v96, v97
	v_max_f32_e32 v177, v177, v178
	v_mfma_f32_32x32x16_bf16 v[18:33], v[162:165], v[196:199], v[18:33]
	ds_read_b128 v[196:199], v141 offset:40960
	v_cmp_ge_f32_e32 vcc, 0x4138aa3b, v177
	s_cmp_eq_u64 vcc, exec
	s_cbranch_scc0 .Lat_rare1_18

; template <bool FIRST> __device__ __forceinline__ void partialSM(f32x16& p0, f32x16& p1, float& mhat, f32x16& negm, float& alpha) {
;   float pa = fmaxf(fmaxf(p0[0], p0[1]), p1[0]), pb = fmaxf(fmaxf(p0[2], p0[3]), p1[1]); pa = fmaxf(fmaxf(pa, p1[2]), p1[3]);
; #pragma unroll
;   for (int r = 4; r < 16; r += 4) { pa = fmaxf(fmaxf(pa, p0[r]), p0[r + 1]); pb = fmaxf(fmaxf(pb, p0[r + 2]), p0[r + 3]); pa = fmaxf(fmaxf(pa, p1[r]), p1[r + 1]); pb = fmaxf(fmaxf(pb, p1[r + 2]), p1[r + 3]); }
;   float pmax = fmaxf(pa, pb);
;   { auto rr = __builtin_amdgcn_permlane32_swap(__float_as_uint(pmax), __float_as_uint(pmax), false, false);
;     pmax = fmaxf(__uint_as_float(rr[0]), __uint_as_float(rr[1])); }
;   if (!FIRST && __builtin_expect(__all(pmax <= THRL), 1)) { alpha = 1.f; }
;   else { const float d = FIRST ? pmax : fmaxf(pmax, 0.f); mhat += d; alpha = FIRST ? 1.f : __builtin_amdgcn_exp2f(-d);
; #pragma unroll
;     for (int r = 0; r < 16; ++r) { p0[r] -= d; p1[r] -= d; }
; #pragma unroll
;     for (int r = 0; r < 16; ++r) negm[r] = -mhat; }
; #pragma unroll
;   for (int r = 0; r < 16; ++r) p0[r] = __builtin_amdgcn_exp2f(p0[r]);
; }
; __device__ __forceinline__ void finishSM(f32x16& p0, f32x16& p1, float alpha, float& l_reg, bf16x8& pa0, bf16x8& pa1, bf16x8& pa2, bf16x8& pa3) {
; #pragma unroll
;   for (int r = 0; r < 16; ++r) p1[r] = __builtin_amdgcn_exp2f(p1[r]);
;   float ps = 0;
; #pragma unroll
;   for (int r = 0; r < 16; ++r) ps += p0[r];
; #pragma unroll
;   for (int r = 0; r < 16; ++r) ps += p1[r];
;   { auto rr = __builtin_amdgcn_permlane32_swap(__float_as_uint(ps), __float_as_uint(ps), false, false);
;     ps = __uint_as_float(rr[0]) + __uint_as_float(rr[1]); }
;   l_reg = l_reg * alpha + ps;
;     ...
;   PK4(p0, 0, pa0); PK4(p0, 8, pa1); PK4(p1, 0, pa2); PK4(p1, 8, pa3);
;     ...
; }
; __device__ __forceinline__ void qkt(f32x16& p0, f32x16& p1, const bf16_t* Ks, const bf16x8* qr, const f32x16& negm, int r32, int hi) {
;   p0 = negm; p1 = negm;
; #pragma unroll
;   for (int d0 = 0; d0 < 6; ++d0) { int cb = (d0 * 16 + hi * 8) * 2;
;     bf16x8 b0 = *reinterpret_cast<const bf16x8*>((const char*)Ks + KSWZ(r32, cb));
;     bf16x8 b1 = *reinterpret_cast<const bf16x8*>((const char*)Ks + KSWZ(32 + r32, cb));
;     p0 = __builtin_amdgcn_mfma_f32_32x32x16_bf16(b0, qr[d0], p0, 0, 0, 0);
;     p1 = __builtin_amdgcn_mfma_f32_32x32x16_bf16(b1, qr[d0], p1, 0, 0, 0); }
; }
.Lat_rr_20:
	s_waitcnt lgkmcnt(0)
	s_barrier
	ds_read_b128 v[200:203], v142 offset:32768
	ds_read_b128 v[204:207], v142 offset:40960
	ds_read_b128 v[208:211], v143 offset:32768
	ds_read_b128 v[212:215], v143 offset:40960
	s_add_i32 m0, s7, 49152
	s_mov_b64 exec, -1
	global_load_lds_dwordx4 v149, s[14:15]
	v_add_u32_e32 v149, 0x38000, v149
	v_mfma_f32_32x32x16_bf16 v[34:49], v[184:187], v[114:117], v[98:113]
	ds_read_b128 v[184:187], v144 offset:32768
	v_exp_f32_e32 v82, v82
	v_exp_f32_e32 v83, v83
	v_exp_f32_e32 v84, v84
	v_exp_f32_e32 v85, v85
	v_exp_f32_e32 v86, v86
	v_mfma_f32_32x32x16_bf16 v[50:65], v[188:191], v[114:117], v[98:113]
	ds_read_b128 v[188:191], v144 offset:40960
	v_exp_f32_e32 v87, v87
	v_exp_f32_e32 v88, v88
	v_exp_f32_e32 v89, v89
	v_exp_f32_e32 v90, v90
	v_exp_f32_e32 v91, v91
	v_mfma_f32_32x32x16_bf16 v[34:49], v[192:195], v[118:121], v[34:49]
	ds_read_b128 v[192:195], v145 offset:32768
	v_exp_f32_e32 v92, v92
	v_exp_f32_e32 v93, v93
	v_exp_f32_e32 v94, v94
	v_exp_f32_e32 v95, v95
	v_exp_f32_e32 v96, v96
	v_mfma_f32_32x32x16_bf16 v[50:65], v[196:199], v[118:121], v[50:65]
	ds_read_b128 v[196:199], v145 offset:40960
	v_exp_f32_e32 v97, v97
	v_cvt_pk_bf16_f32 v158, v66, v67
	v_cvt_pk_bf16_f32 v159, v68, v69
	v_cvt_pk_bf16_f32 v160, v70, v71
	v_cvt_pk_bf16_f32 v161, v72, v73
	s_waitcnt lgkmcnt(6)
	v_mfma_f32_32x32x16_bf16 v[34:49], v[200:203], v[122:125], v[34:49]
	ds_read_b64_tr_b16 v[200:201], v150 offset:24576
	ds_read_b64_tr_b16 v[202:203], v150 offset:26624
	v_cvt_pk_bf16_f32 v162, v74, v75
	v_cvt_pk_bf16_f32 v163, v76, v77
	v_cvt_pk_bf16_f32 v164, v78, v79
	v_cvt_pk_bf16_f32 v165, v80, v81
	v_add_f32_e32 v181, v181, v82
	v_mfma_f32_32x32x16_bf16 v[50:65], v[204:207], v[122:125], v[50:65]
	ds_read_b64_tr_b16 v[204:205], v150 offset:25088
	ds_read_b64_tr_b16 v[206:207], v150 offset:27136
	v_add_f32_e32 v182, v182, v83
	v_add_f32_e32 v183, v183, v84
	v_add_f32_e32 v216, v216, v85
	v_add_f32_e32 v181, v181, v86
	v_add_f32_e32 v182, v182, v87
	s_waitcnt lgkmcnt(8)
	v_mfma_f32_32x32x16_bf16 v[34:49], v[208:211], v[126:129], v[34:49]
	ds_read_b64_tr_b16 v[208:209], v150 offset:28672
	ds_read_b64_tr_b16 v[210:211], v150 offset:30720
	v_add_f32_e32 v183, v183, v88
	v_add_f32_e32 v216, v216, v89
	v_add_f32_e32 v181, v181, v90
	v_add_f32_e32 v182, v182, v91
	v_add_f32_e32 v183, v183, v92
	v_mfma_f32_32x32x16_bf16 v[50:65], v[212:215], v[126:129], v[50:65]
	ds_read_b64_tr_b16 v[212:213], v150 offset:29184
	ds_read_b64_tr_b16 v[214:215], v150 offset:31232
	v_add_f32_e32 v216, v216, v93
	v_add_f32_e32 v181, v181, v94
	v_add_f32_e32 v182, v182, v95
	v_add_f32_e32 v183, v183, v96
	v_add_f32_e32 v216, v216, v97
	s_waitcnt lgkmcnt(10)
	v_mfma_f32_32x32x16_bf16 v[34:49], v[184:187], v[130:133], v[34:49]
	ds_read_b64_tr_b16 v[184:185], v150 offset:16384
	ds_read_b64_tr_b16 v[186:187], v150 offset:18432
	v_add_f32_e32 v181, v181, v182
	v_add_f32_e32 v183, v183, v216
	v_add_f32_e32 v181, v181, v183
	v_add_f32_e32 v174, v174, v181
	v_cvt_pk_bf16_f32 v166, v82, v83
	v_mfma_f32_32x32x16_bf16 v[50:65], v[188:191], v[130:133], v[50:65]
	ds_read_b64_tr_b16 v[188:189], v150 offset:16896
	ds_read_b64_tr_b16 v[190:191], v150 offset:18944
	v_cvt_pk_bf16_f32 v167, v84, v85
	v_cvt_pk_bf16_f32 v168, v86, v87
	v_cvt_pk_bf16_f32 v169, v88, v89
	v_cvt_pk_bf16_f32 v170, v90, v91
	v_cvt_pk_bf16_f32 v171, v92, v93
	s_waitcnt lgkmcnt(12)
	v_mfma_f32_32x32x16_bf16 v[34:49], v[192:195], v[134:137], v[34:49]
	ds_read_b64_tr_b16 v[192:193], v150 offset:20480
	ds_read_b64_tr_b16 v[194:195], v150 offset:22528
	v_cvt_pk_bf16_f32 v172, v94, v95
	v_cvt_pk_bf16_f32 v173, v96, v97
	v_mfma_f32_32x32x16_bf16 v[50:65], v[196:199], v[134:137], v[50:65]
	ds_read_b64_tr_b16 v[196:197], v150 offset:20992
	s_waitcnt lgkmcnt(14)
	ds_read_b64_tr_b16 v[198:199], v150 offset:23040
	s_waitcnt lgkmcnt(4)
	v_mfma_f32_32x32x16_bf16 v[2:17], v[158:161], v[184:187], v[2:17]
	ds_read_b128 v[184:187], v140 offset:49152
	v_mfma_f32_32x32x16_bf16 v[18:33], v[158:161], v[188:191], v[18:33]
	ds_read_b128 v[188:191], v140 offset:57344
	v_max3_f32 v177, v34, v35, v36
	v_max3_f32 v178, v37, v38, v39
	v_max3_f32 v177, v177, v40, v41
	v_max3_f32 v178, v178, v42, v43
	v_max3_f32 v177, v177, v44, v45
	v_max3_f32 v178, v178, v46, v47
	v_max3_f32 v177, v177, v48, v49
	v_max3_f32 v178, v178, v50, v51
	s_waitcnt lgkmcnt(2)
	v_mfma_f32_32x32x16_bf16 v[2:17], v[162:165], v[192:195], v[2:17]
	ds_read_b128 v[192:195], v141 offset:49152
	v_max3_f32 v177, v177, v52, v53
	v_max3_f32 v178, v178, v54, v55
	v_max3_f32 v177, v177, v56, v57
	v_max3_f32 v178, v178, v58, v59
	v_max3_f32 v177, v177, v60, v61
	v_max3_f32 v178, v178, v62, v63
	v_max3_f32 v177, v177, v64, v65
	v_max_f32_e32 v177, v177, v178
	v_mfma_f32_32x32x16_bf16 v[18:33], v[162:165], v[196:199], v[18:33]
	ds_read_b128 v[196:199], v141 offset:57344
	v_cmp_ge_f32_e32 vcc, 0x4138aa3b, v177
	s_cmp_eq_u64 vcc, exec
	s_cbranch_scc0 .Lat_rare1_22

; template <bool FIRST> __device__ __forceinline__ void partialSM(f32x16& p0, f32x16& p1, float& mhat, f32x16& negm, float& alpha) {
;   float pa = fmaxf(fmaxf(p0[0], p0[1]), p1[0]), pb = fmaxf(fmaxf(p0[2], p0[3]), p1[1]); pa = fmaxf(fmaxf(pa, p1[2]), p1[3]);
; #pragma unroll
;   for (int r = 4; r < 16; r += 4) { pa = fmaxf(fmaxf(pa, p0[r]), p0[r + 1]); pb = fmaxf(fmaxf(pb, p0[r + 2]), p0[r + 3]); pa = fmaxf(fmaxf(pa, p1[r]), p1[r + 1]); pb = fmaxf(fmaxf(pb, p1[r + 2]), p1[r + 3]); }
;   float pmax = fmaxf(pa, pb);
;   { auto rr = __builtin_amdgcn_permlane32_swap(__float_as_uint(pmax), __float_as_uint(pmax), false, false);
;     pmax = fmaxf(__uint_as_float(rr[0]), __uint_as_float(rr[1])); }
;   if (!FIRST && __builtin_expect(__all(pmax <= THRL), 1)) { alpha = 1.f; }
;   else { const float d = FIRST ? pmax : fmaxf(pmax, 0.f); mhat += d; alpha = FIRST ? 1.f : __builtin_amdgcn_exp2f(-d);
; #pragma unroll
;     for (int r = 0; r < 16; ++r) { p0[r] -= d; p1[r] -= d; }
; #pragma unroll
;     for (int r = 0; r < 16; ++r) negm[r] = -mhat; }
; #pragma unroll
;   for (int r = 0; r < 16; ++r) p0[r] = __builtin_amdgcn_exp2f(p0[r]);
; }
; __device__ __forceinline__ void finishSM(f32x16& p0, f32x16& p1, float alpha, float& l_reg, bf16x8& pa0, bf16x8& pa1, bf16x8& pa2, bf16x8& pa3) {
; #pragma unroll
;   for (int r = 0; r < 16; ++r) p1[r] = __builtin_amdgcn_exp2f(p1[r]);
;   float ps = 0;
; #pragma unroll
;   for (int r = 0; r < 16; ++r) ps += p0[r];
; #pragma unroll
;   for (int r = 0; r < 16; ++r) ps += p1[r];
;   { auto rr = __builtin_amdgcn_permlane32_swap(__float_as_uint(ps), __float_as_uint(ps), false, false);
;     ps = __uint_as_float(rr[0]) + __uint_as_float(rr[1]); }
;   l_reg = l_reg * alpha + ps;
;     ...
;   PK4(p0, 0, pa0); PK4(p0, 8, pa1); PK4(p1, 0, pa2); PK4(p1, 8, pa3);
;     ...
; }
; __device__ __forceinline__ void qkt(f32x16& p0, f32x16& p1, const bf16_t* Ks, const bf16x8* qr, const f32x16& negm, int r32, int hi) {
;   p0 = negm; p1 = negm;
; #pragma unroll
;   for (int d0 = 0; d0 < 6; ++d0) { int cb = (d0 * 16 + hi * 8) * 2;
;     bf16x8 b0 = *reinterpret_cast<const bf16x8*>((const char*)Ks + KSWZ(r32, cb));
;     bf16x8 b1 = *reinterpret_cast<const bf16x8*>((const char*)Ks + KSWZ(32 + r32, cb));
;     p0 = __builtin_amdgcn_mfma_f32_32x32x16_bf16(b0, qr[d0], p0, 0, 0, 0);
;     p1 = __builtin_amdgcn_mfma_f32_32x32x16_bf16(b1, qr[d0], p1, 0, 0, 0); }
; }
.Lat_rr_24:
	s_waitcnt lgkmcnt(0)
	s_barrier
	ds_read_b128 v[200:203], v142 offset:49152
	ds_read_b128 v[204:207], v142 offset:57344
	ds_read_b128 v[208:211], v143 offset:49152
	ds_read_b128 v[212:215], v143 offset:57344
	v_mfma_f32_32x32x16_bf16 v[66:81], v[184:187], v[114:117], v[98:113]
	ds_read_b128 v[184:187], v144 offset:49152
	v_exp_f32_e32 v50, v50
	v_exp_f32_e32 v51, v51
	v_exp_f32_e32 v52, v52
	v_exp_f32_e32 v53, v53
	v_exp_f32_e32 v54, v54
	v_mfma_f32_32x32x16_bf16 v[82:97], v[188:191], v[114:117], v[98:113]
	ds_read_b128 v[188:191], v144 offset:57344
	v_exp_f32_e32 v55, v55
	v_exp_f32_e32 v56, v56
	v_exp_f32_e32 v57, v57
	v_exp_f32_e32 v58, v58
	v_exp_f32_e32 v59, v59
	v_mfma_f32_32x32x16_bf16 v[66:81], v[192:195], v[118:121], v[66:81]
	ds_read_b128 v[192:195], v145 offset:49152
	v_exp_f32_e32 v60, v60
	v_exp_f32_e32 v61, v61
	v_exp_f32_e32 v62, v62
	v_exp_f32_e32 v63, v63
	v_exp_f32_e32 v64, v64
	v_mfma_f32_32x32x16_bf16 v[82:97], v[196:199], v[118:121], v[82:97]
	ds_read_b128 v[196:199], v145 offset:57344
	v_exp_f32_e32 v65, v65
	v_cvt_pk_bf16_f32 v158, v34, v35
	v_cvt_pk_bf16_f32 v159, v36, v37
	v_cvt_pk_bf16_f32 v160, v38, v39
	v_cvt_pk_bf16_f32 v161, v40, v41
	s_waitcnt lgkmcnt(6)
	v_mfma_f32_32x32x16_bf16 v[66:81], v[200:203], v[122:125], v[66:81]
	ds_read_b64_tr_b16 v[200:201], v150 offset:40960
	ds_read_b64_tr_b16 v[202:203], v150 offset:43008
	v_cvt_pk_bf16_f32 v162, v42, v43
	v_cvt_pk_bf16_f32 v163, v44, v45
	v_cvt_pk_bf16_f32 v164, v46, v47
	v_cvt_pk_bf16_f32 v165, v48, v49
	v_add_f32_e32 v181, v181, v50
	v_mfma_f32_32x32x16_bf16 v[82:97], v[204:207], v[122:125], v[82:97]
	ds_read_b64_tr_b16 v[204:205], v150 offset:41472
	ds_read_b64_tr_b16 v[206:207], v150 offset:43520
	v_add_f32_e32 v182, v182, v51
	v_add_f32_e32 v183, v183, v52
	v_add_f32_e32 v216, v216, v53
	v_add_f32_e32 v181, v181, v54
	v_add_f32_e32 v182, v182, v55
	s_waitcnt lgkmcnt(8)
	v_mfma_f32_32x32x16_bf16 v[66:81], v[208:211], v[126:129], v[66:81]
	ds_read_b64_tr_b16 v[208:209], v150 offset:45056
	ds_read_b64_tr_b16 v[210:211], v150 offset:47104
	v_add_f32_e32 v183, v183, v56
	v_add_f32_e32 v216, v216, v57
	v_add_f32_e32 v181, v181, v58
	v_add_f32_e32 v182, v182, v59
	v_add_f32_e32 v183, v183, v60
	v_mfma_f32_32x32x16_bf16 v[82:97], v[212:215], v[126:129], v[82:97]
	ds_read_b64_tr_b16 v[212:213], v150 offset:45568
	ds_read_b64_tr_b16 v[214:215], v150 offset:47616
	v_add_f32_e32 v216, v216, v61
	v_add_f32_e32 v181, v181, v62
	v_add_f32_e32 v182, v182, v63
	v_add_f32_e32 v183, v183, v64
	v_add_f32_e32 v216, v216, v65
	s_waitcnt lgkmcnt(10)
	v_mfma_f32_32x32x16_bf16 v[66:81], v[184:187], v[130:133], v[66:81]
	ds_read_b64_tr_b16 v[184:185], v150 offset:32768
	ds_read_b64_tr_b16 v[186:187], v150 offset:34816
	v_add_f32_e32 v181, v181, v182
	v_add_f32_e32 v183, v183, v216
	v_add_f32_e32 v181, v181, v183
	v_add_f32_e32 v174, v174, v181
	v_cvt_pk_bf16_f32 v166, v50, v51
	v_mfma_f32_32x32x16_bf16 v[82:97], v[188:191], v[130:133], v[82:97]
	ds_read_b64_tr_b16 v[188:189], v150 offset:33280
	ds_read_b64_tr_b16 v[190:191], v150 offset:35328
	v_cvt_pk_bf16_f32 v167, v52, v53
	v_cvt_pk_bf16_f32 v168, v54, v55
	v_cvt_pk_bf16_f32 v169, v56, v57
	v_cvt_pk_bf16_f32 v170, v58, v59
	v_cvt_pk_bf16_f32 v171, v60, v61
	s_waitcnt lgkmcnt(12)
	v_mfma_f32_32x32x16_bf16 v[66:81], v[192:195], v[134:137], v[66:81]
	ds_read_b64_tr_b16 v[192:193], v150 offset:36864
	ds_read_b64_tr_b16 v[194:195], v150 offset:38912
	v_cvt_pk_bf16_f32 v172, v62, v63
	v_cvt_pk_bf16_f32 v173, v64, v65
	v_mfma_f32_32x32x16_bf16 v[82:97], v[196:199], v[134:137], v[82:97]
	ds_read_b64_tr_b16 v[196:197], v150 offset:37376
	s_waitcnt lgkmcnt(14)
	ds_read_b64_tr_b16 v[198:199], v150 offset:39424
	s_waitcnt lgkmcnt(4)
	v_mfma_f32_32x32x16_bf16 v[2:17], v[158:161], v[184:187], v[2:17]
	v_mfma_f32_32x32x16_bf16 v[18:33], v[158:161], v[188:191], v[18:33]
	s_nop 0
	v_max3_f32 v177, v66, v67, v68
	v_max3_f32 v178, v69, v70, v71
	v_max3_f32 v177, v177, v72, v73
	v_max3_f32 v178, v178, v74, v75
	v_max3_f32 v177, v177, v76, v77
	v_max3_f32 v178, v178, v78, v79
	v_max3_f32 v177, v177, v80, v81
	v_max3_f32 v178, v178, v82, v83
	s_waitcnt lgkmcnt(0)
	v_mfma_f32_32x32x16_bf16 v[2:17], v[162:165], v[192:195], v[2:17]
	v_max3_f32 v177, v177, v84, v85
	v_max3_f32 v178, v178, v86, v87
	v_max3_f32 v177, v177, v88, v89
	v_max3_f32 v178, v178, v90, v91
	v_max3_f32 v177, v177, v92, v93
	v_max3_f32 v178, v178, v94, v95
	v_max3_f32 v177, v177, v96, v97
	v_max_f32_e32 v177, v177, v178
	v_mfma_f32_32x32x16_bf16 v[18:33], v[162:165], v[196:199], v[18:33]
	v_cmp_ge_f32_e32 vcc, 0x4138aa3b, v177
	s_cmp_eq_u64 vcc, exec
	s_cbranch_scc0 .Lat_rare1_26

; #define SBAR() __builtin_amdgcn_sched_barrier(0)
; __device__ __forceinline__ void finishSM(f32x16& p0, f32x16& p1, float alpha, float& l_reg, bf16x8& pa0, bf16x8& pa1, bf16x8& pa2, bf16x8& pa3) {
; #pragma unroll
;   for (int r = 0; r < 16; ++r) p1[r] = __builtin_amdgcn_exp2f(p1[r]);
;   float ps = 0;
; #pragma unroll
;   for (int r = 0; r < 16; ++r) ps += p0[r];
; #pragma unroll
;   for (int r = 0; r < 16; ++r) ps += p1[r];
;   { auto rr = __builtin_amdgcn_permlane32_swap(__float_as_uint(ps), __float_as_uint(ps), false, false);
;     ps = __uint_as_float(rr[0]) + __uint_as_float(rr[1]); }
;   l_reg = l_reg * alpha + ps;
;     ...
;   PK4(p0, 0, pa0); PK4(p0, 8, pa1); PK4(p1, 0, pa2); PK4(p1, 8, pa3);
;     ...
; }
; template <int D0> __device__ __forceinline__ void pv_one(f32x16& od, int vb, bf16x8 pa0, bf16x8 pa1, bf16x8 pa2, bf16x8 pa3) {
;   const s16x4 l0 = tr_read<v_rd_off(D0, 0, 0)>(vb), h0 = tr_read<v_rd_off(D0, 0, 1)>(vb), l1 = tr_read<v_rd_off(D0, 1, 0)>(vb), h1 = tr_read<v_rd_off(D0, 1, 1)>(vb);
;   const s16x4 l2 = tr_read<v_rd_off(D0, 2, 0)>(vb), h2 = tr_read<v_rd_off(D0, 2, 1)>(vb), l3 = tr_read<v_rd_off(D0, 3, 0)>(vb), h3 = tr_read<v_rd_off(D0, 3, 1)>(vb);
;   asm volatile("s_waitcnt lgkmcnt(0)" ::: "memory"); SBAR();
;     ...
;   od = __builtin_amdgcn_mfma_f32_32x32x16_bf16(pa0, PK(l0, h0), od, 0, 0, 0);
;   od = __builtin_amdgcn_mfma_f32_32x32x16_bf16(pa1, PK(l1, h1), od, 0, 0, 0);
;   od = __builtin_amdgcn_mfma_f32_32x32x16_bf16(pa2, PK(l2, h2), od, 0, 0, 0);
;   od = __builtin_amdgcn_mfma_f32_32x32x16_bf16(pa3, PK(l3, h3), od, 0, 0, 0);
;     ...
; }
; __device__ __forceinline__ void pv_d0(f32x16* o, int vb, bf16x8 pa0, bf16x8 pa1, bf16x8 pa2, bf16x8 pa3) {
;   pv_one<0>(o[0], vb, pa0, pa1, pa2, pa3); pv_one<1>(o[1], vb, pa0, pa1, pa2, pa3);
; }
.Lat_rr_28:
	s_barrier
	ds_read_b64_tr_b16 v[184:185], v150 offset:49152
	ds_read_b64_tr_b16 v[186:187], v150 offset:51200
	ds_read_b64_tr_b16 v[188:189], v150 offset:49664
	ds_read_b64_tr_b16 v[190:191], v150 offset:51712
	ds_read_b64_tr_b16 v[192:193], v150 offset:53248
	ds_read_b64_tr_b16 v[194:195], v150 offset:55296
	ds_read_b64_tr_b16 v[196:197], v150 offset:53760
	ds_read_b64_tr_b16 v[198:199], v150 offset:55808
	v_exp_f32_e32 v82, v82
	v_exp_f32_e32 v83, v83
	v_exp_f32_e32 v84, v84
	v_exp_f32_e32 v85, v85
	v_exp_f32_e32 v86, v86
	v_exp_f32_e32 v87, v87
	v_exp_f32_e32 v88, v88
	v_exp_f32_e32 v89, v89
	v_exp_f32_e32 v90, v90
	v_exp_f32_e32 v91, v91
	v_exp_f32_e32 v92, v92
	v_exp_f32_e32 v93, v93
	v_exp_f32_e32 v94, v94
	v_exp_f32_e32 v95, v95
	v_exp_f32_e32 v96, v96
	v_exp_f32_e32 v97, v97
	v_cvt_pk_bf16_f32 v158, v66, v67
	v_cvt_pk_bf16_f32 v159, v68, v69
	v_cvt_pk_bf16_f32 v160, v70, v71
	v_cvt_pk_bf16_f32 v161, v72, v73
	v_cvt_pk_bf16_f32 v162, v74, v75
	v_cvt_pk_bf16_f32 v163, v76, v77
	v_cvt_pk_bf16_f32 v164, v78, v79
	v_cvt_pk_bf16_f32 v165, v80, v81
	v_add_f32_e32 v181, v181, v82
	v_add_f32_e32 v182, v182, v83
	v_add_f32_e32 v183, v183, v84
	v_add_f32_e32 v216, v216, v85
	v_add_f32_e32 v181, v181, v86
	v_add_f32_e32 v182, v182, v87
	ds_read_b64_tr_b16 v[200:201], v150 offset:57344
	ds_read_b64_tr_b16 v[202:203], v150 offset:59392
	ds_read_b64_tr_b16 v[204:205], v150 offset:57856
	ds_read_b64_tr_b16 v[206:207], v150 offset:59904
	ds_read_b64_tr_b16 v[208:209], v150 offset:61440
	ds_read_b64_tr_b16 v[210:211], v150 offset:63488
	ds_read_b64_tr_b16 v[212:213], v150 offset:61952
	s_waitcnt lgkmcnt(14)
	ds_read_b64_tr_b16 v[214:215], v150 offset:64000
	v_add_f32_e32 v183, v183, v88
	v_add_f32_e32 v216, v216, v89
	v_add_f32_e32 v181, v181, v90
	v_add_f32_e32 v182, v182, v91
	v_add_f32_e32 v183, v183, v92
	v_add_f32_e32 v216, v216, v93
	v_add_f32_e32 v181, v181, v94
	v_add_f32_e32 v182, v182, v95
	v_add_f32_e32 v183, v183, v96
	v_add_f32_e32 v216, v216, v97
	v_add_f32_e32 v181, v181, v182
	v_add_f32_e32 v183, v183, v216
	v_add_f32_e32 v181, v181, v183
	v_add_f32_e32 v174, v174, v181
	v_cvt_pk_bf16_f32 v166, v82, v83
	v_cvt_pk_bf16_f32 v167, v84, v85
	v_cvt_pk_bf16_f32 v168, v86, v87
	v_cvt_pk_bf16_f32 v169, v88, v89
	v_cvt_pk_bf16_f32 v170, v90, v91
	v_cvt_pk_bf16_f32 v171, v92, v93
	v_cvt_pk_bf16_f32 v172, v94, v95
	v_cvt_pk_bf16_f32 v173, v96, v97
	s_waitcnt lgkmcnt(12)
	v_mfma_f32_32x32x16_bf16 v[2:17], v[158:161], v[184:187], v[2:17]
	v_mfma_f32_32x32x16_bf16 v[18:33], v[158:161], v[188:191], v[18:33]
	s_waitcnt lgkmcnt(8)
	v_mfma_f32_32x32x16_bf16 v[2:17], v[162:165], v[192:195], v[2:17]
	v_mfma_f32_32x32x16_bf16 v[18:33], v[162:165], v[196:199], v[18:33]
	s_waitcnt lgkmcnt(4)
	v_mfma_f32_32x32x16_bf16 v[2:17], v[166:169], v[200:203], v[2:17]
	v_mfma_f32_32x32x16_bf16 v[18:33], v[166:169], v[204:207], v[18:33]
	s_waitcnt lgkmcnt(0)
	v_mfma_f32_32x32x16_bf16 v[2:17], v[170:173], v[208:211], v[2:17]
	v_mfma_f32_32x32x16_bf16 v[18:33], v[170:173], v[212:215], v[18:33]
	s_waitcnt vmcnt(0)
	s_cmp_lg_u32 s9, 0
	s_cbranch_scc1 .Lat_rare2_30

; template <bool FIRST> __device__ __forceinline__ void partialSM(f32x16& p0, f32x16& p1, float& mhat, f32x16& negm, float& alpha) {
;     ...
;   if (!FIRST && __builtin_expect(__all(pmax <= THRL), 1)) { alpha = 1.f; }
;   else { const float d = FIRST ? pmax : fmaxf(pmax, 0.f); mhat += d; alpha = FIRST ? 1.f : __builtin_amdgcn_exp2f(-d);
; #pragma unroll
;     for (int r = 0; r < 16; ++r) { p0[r] -= d; p1[r] -= d; }
; #pragma unroll
;     for (int r = 0; r < 16; ++r) negm[r] = -mhat; }
.Lat_rareI_34:
	v_mov_b32_e32 v178, v177
	s_nop 1
	v_permlane32_swap_b32_e32 v177, v178
	v_max_f32_e32 v177, v177, v178
	v_max_f32_e32 v177, 0, v177
	v_exp_f32_e64 v178, -v177
	v_add_f32_e32 v151, v151, v177
	v_sub_f32_e32 v34, v34, v177
	v_sub_f32_e32 v35, v35, v177
	v_sub_f32_e32 v36, v36, v177
	v_sub_f32_e32 v37, v37, v177
	v_sub_f32_e32 v38, v38, v177
	v_sub_f32_e32 v39, v39, v177
	v_sub_f32_e32 v40, v40, v177
	v_sub_f32_e32 v41, v41, v177
	v_sub_f32_e32 v42, v42, v177
	v_sub_f32_e32 v43, v43, v177
	v_sub_f32_e32 v44, v44, v177
	v_sub_f32_e32 v45, v45, v177
	v_sub_f32_e32 v46, v46, v177
	v_sub_f32_e32 v47, v47, v177
	v_sub_f32_e32 v48, v48, v177
	v_sub_f32_e32 v49, v49, v177
	v_sub_f32_e32 v50, v50, v177
	v_sub_f32_e32 v51, v51, v177
	v_sub_f32_e32 v52, v52, v177
	v_sub_f32_e32 v53, v53, v177
	v_sub_f32_e32 v54, v54, v177
	v_sub_f32_e32 v55, v55, v177
	v_sub_f32_e32 v56, v56, v177
	v_sub_f32_e32 v57, v57, v177
	v_sub_f32_e32 v58, v58, v177
	v_sub_f32_e32 v59, v59, v177
	v_sub_f32_e32 v60, v60, v177
	v_sub_f32_e32 v61, v61, v177
	v_sub_f32_e32 v62, v62, v177
	v_sub_f32_e32 v63, v63, v177
	v_sub_f32_e32 v64, v64, v177
	v_sub_f32_e32 v65, v65, v177
	v_xor_b32_e32 v98, 0x80000000, v151
	v_mov_b32_e32 v99, v98
	v_mov_b32_e32 v100, v98
	v_mov_b32_e32 v101, v98
	v_mov_b32_e32 v102, v98
	v_mov_b32_e32 v103, v98
	v_mov_b32_e32 v104, v98
	v_mov_b32_e32 v105, v98
	v_mov_b32_e32 v106, v98
	v_mov_b32_e32 v107, v98
	v_mov_b32_e32 v108, v98
	v_mov_b32_e32 v109, v98
	v_mov_b32_e32 v110, v98
	v_mov_b32_e32 v111, v98
	v_mov_b32_e32 v112, v98
	v_mov_b32_e32 v113, v98
	v_mul_f32_e32 v174, v174, v178
	s_mov_b32 exec_hi, 0
	ds_write_b32 v175, v178 offset:128
	s_mov_b64 exec, -1
	s_mov_b32 s9, 1
	s_nop 3
	s_cmp_eq_u32 s10, 1
	s_cbranch_scc1 .Lat_ri_5
	s_cmp_eq_u32 s10, 3
	s_cbranch_scc1 .Lat_ri_13
	s_cmp_eq_u32 s10, 5
	s_cbranch_scc1 .Lat_ri_21
	s_endpgm
.Lat_rareI_66:
	v_mov_b32_e32 v178, v177
	s_nop 1
	v_permlane32_swap_b32_e32 v177, v178
	v_max_f32_e32 v177, v177, v178
	v_max_f32_e32 v177, 0, v177
	v_exp_f32_e64 v178, -v177
	v_add_f32_e32 v151, v151, v177
	v_sub_f32_e32 v66, v66, v177
	v_sub_f32_e32 v67, v67, v177
	v_sub_f32_e32 v68, v68, v177
	v_sub_f32_e32 v69, v69, v177
	v_sub_f32_e32 v70, v70, v177
	v_sub_f32_e32 v71, v71, v177
	v_sub_f32_e32 v72, v72, v177
	v_sub_f32_e32 v73, v73, v177
	v_sub_f32_e32 v74, v74, v177
	v_sub_f32_e32 v75, v75, v177
	v_sub_f32_e32 v76, v76, v177
	v_sub_f32_e32 v77, v77, v177
	v_sub_f32_e32 v78, v78, v177
	v_sub_f32_e32 v79, v79, v177
	v_sub_f32_e32 v80, v80, v177
	v_sub_f32_e32 v81, v81, v177
	v_sub_f32_e32 v82, v82, v177
	v_sub_f32_e32 v83, v83, v177
	v_sub_f32_e32 v84, v84, v177
	v_sub_f32_e32 v85, v85, v177
	v_sub_f32_e32 v86, v86, v177
	v_sub_f32_e32 v87, v87, v177
	v_sub_f32_e32 v88, v88, v177
	v_sub_f32_e32 v89, v89, v177
	v_sub_f32_e32 v90, v90, v177
	v_sub_f32_e32 v91, v91, v177
	v_sub_f32_e32 v92, v92, v177
	v_sub_f32_e32 v93, v93, v177
	v_sub_f32_e32 v94, v94, v177
	v_sub_f32_e32 v95, v95, v177
	v_sub_f32_e32 v96, v96, v177
	v_sub_f32_e32 v97, v97, v177
	v_xor_b32_e32 v98, 0x80000000, v151
	v_mov_b32_e32 v99, v98
	v_mov_b32_e32 v100, v98
	v_mov_b32_e32 v101, v98
	v_mov_b32_e32 v102, v98
	v_mov_b32_e32 v103, v98
	v_mov_b32_e32 v104, v98
	v_mov_b32_e32 v105, v98
	v_mov_b32_e32 v106, v98
	v_mov_b32_e32 v107, v98
	v_mov_b32_e32 v108, v98
	v_mov_b32_e32 v109, v98
	v_mov_b32_e32 v110, v98
	v_mov_b32_e32 v111, v98
	v_mov_b32_e32 v112, v98
	v_mov_b32_e32 v113, v98
	v_mul_f32_e32 v174, v174, v178
	s_mov_b32 exec_hi, 0
	ds_write_b32 v175, v178 offset:128
	s_mov_b64 exec, -1
	s_mov_b32 s9, 1
	s_nop 3
	s_cmp_eq_u32 s10, 0
	s_cbranch_scc1 .Lat_ri_1
	s_cmp_eq_u32 s10, 2
	s_cbranch_scc1 .Lat_ri_9
	s_cmp_eq_u32 s10, 4
	s_cbranch_scc1 .Lat_ri_17
	s_cmp_eq_u32 s10, 6
	s_cbranch_scc1 .Lat_ri_25
	s_endpgm
